# xo GEMM epilogue: stats/src loads prefetched 2 row-blocks ahead, LN gamma/beta staged in LDS
# speedup vs baseline: 1.0157x; 1.0157x over previous
; __device__ __forceinline__ u32x2 pk4(f32x4 v) { u32x2 r; r.x = pk2(v.x, v.y); r.y = pk2(v.z, v.w); return r; }
;     __device__ __forceinline__ void operator()(int row, int col, f32x4 v, int, float&, float&) const { *(u32x2*)(O + (size_t)row * ldc + col) = pk4(v * s); }
; __device__ __forceinline__ void stats_main(const float* stm, int row, int fq, float& mu, float& rs) {
;     const f32x4* p = (const f32x4*)(stm + (size_t)row * 32 + fq * 8);
;     const f32x4 a = p[0], b = p[1];
;     float s1 = (a.x + a.z) + (b.x + b.z), s2 = (a.y + a.w) + (b.y + b.w);
;     s1 += __shfl_xor(s1, 16); s2 += __shfl_xor(s2, 16); s1 += __shfl_xor(s1, 32); s2 += __shfl_xor(s2, 32);
;     mu = s1 * (1.f / DM); rs = __builtin_amdgcn_rsqf(fmaxf(s2 * (1.f / DM) - mu * mu, 0.f) + LN_EPS);
; }
;     __device__ __forceinline__ void operator()(const f32x4 (&acc)[2][2][4][2], const pg8::Unit& u, int wr, int wc, int fr, int fq) const {
; #pragma unroll
;         for (int ai = 0; ai < 2; ++ai)
; #pragma unroll
;             for (int m = 0; m < 4; ++m) {
;                 const int row = u.pm * 256 + ai * 128 + wr * 64 + m * 16 + fr;
;                 float mu = 0.f, rs = 1.f; if (ln) stats_main(stm_p, row, fq, mu, rs);
;                 float s1 = 0.f, s2 = 0.f;
; #pragma unroll
;                 for (int bj = 0; bj < 2; ++bj)
; #pragma unroll
;                     for (int n = 0; n < 2; ++n) {
;                         const int col = u.pn * 256 + bj * 128 + wc * 32 + n * 16 + fq * 4;
;                         const u32x2 raw = *(const u32x2*)(src + (size_t)row * DM + col);
;                         f32x4 x = (f32x4){bflo(raw.x), bfhi(raw.x), bflo(raw.y), bfhi(raw.y)};
;                         if (ln) x = (x - mu) * rs * *(const f32x4*)(g + col) + *(const f32x4*)(b + col);
;                         const u32x2 pz = pk4(x * ALPHA + acc[ai][bj][m][n]);
;                         *(u32x2*)(dst + (size_t)row * DM + col) = pz;
;                         const float z0 = bflo(pz.x), z1 = bfhi(pz.x), z2 = bflo(pz.y), z3 = bfhi(pz.y);
;                         s1 += (z0 + z1) + (z2 + z3); s2 += (z0 * z0 + z1 * z1) + (z2 * z2 + z3 * z3);
;                     }
.LBB0_2203:
	v_readlane_b32 s70, v250, 30
	v_readlane_b32 s71, v250, 31
	v_and_b32_e32 v244, 0xfffffff0, v166
	v_lshl_add_u32 v244, s22, 8, v244
	v_and_b32_e32 v245, 31, v219
	v_add_u32_e32 v244, v244, v245
	v_lshrrev_b32_e32 v245, 5, v219
	v_lshl_add_u32 v244, v245, 7, v244
	v_lshlrev_b32_e32 v244, 2, v244
	global_load_dword v214, v244, s[46:47]
	global_load_dword v215, v244, s[48:49]
	v_lshl_add_u32 v245, s23, 8, v164
	v_lshl_add_u32 v244, s22, 8, v166
	v_lshlrev_b32_e32 v242, 11, v245
	v_lshl_add_u32 v242, v244, 1, v242
	v_lshlrev_b32_e32 v246, 7, v245
	v_mov_b32_e32 v247, 0
	v_lshlrev_b32_e32 v248, 7, v245
	v_mov_b32_e32 v249, 0
	v_add_u32_e32 v246, 0x1000, v246
	v_add_u32_e32 v248, 0x5000, v248
	v_lshl_add_u64 v[246:247], v[246:247], 0, v[134:135]
	v_lshl_add_u64 v[248:249], v[248:249], 0, v[134:135]
	global_load_dwordx4 v[190:193], v[246:247], off offset:-4080
	global_load_dwordx4 v[194:197], v[246:247], off offset:-4096
	global_load_dwordx2 v[198:199], v242, s[70:71]
	global_load_dwordx2 v[200:201], v242, s[70:71] offset:32
	global_load_dwordx2 v[202:203], v242, s[70:71] offset:256
	global_load_dwordx2 v[204:205], v242, s[70:71] offset:288
	v_lshrrev_b32_e32 v245, 6, v164
	v_lshrrev_b32_e32 v244, 5, v166
	v_lshl_add_u32 v245, v245, 2, v244
	v_lshlrev_b32_e32 v245, 9, v245
	v_and_b32_e32 v244, 12, v166
	v_lshl_add_u32 v244, v244, 2, v245
	v_add_u32_e32 v244, 0x20000, v244
	v_lshl_add_u32 v245, v219, 2, v245
	v_add_u32_e32 v245, 0x20000, v245
	s_waitcnt vmcnt(7)
	ds_write_b32 v245, v214
	s_waitcnt vmcnt(6)
	ds_write_b32 v245, v215 offset:256
	v_add_u32_e32 v243, 0x8000, v242
	global_load_dwordx4 v[206:209], v[246:247], off offset:-2032
	global_load_dwordx4 v[214:217], v[246:247], off offset:-2048
	global_load_dwordx2 v[234:235], v243, s[70:71]
	global_load_dwordx2 v[236:237], v243, s[70:71] offset:32
	global_load_dwordx2 v[238:239], v243, s[70:71] offset:256
	global_load_dwordx2 v[240:241], v243, s[70:71] offset:288
	s_waitcnt lgkmcnt(0)
	v_and_b32_e32 v140, 64, v219
	v_lshl_add_u32 v146, s23, 8, v164
	v_xor_b32_e32 v3, 16, v219
	v_add_u32_e32 v140, 64, v140
	v_cmp_lt_i32_e32 vcc, v3, v140
	v_ashrrev_i32_e32 v147, 31, v146
	v_lshlrev_b64 v[148:149], 7, v[146:147]
	v_cndmask_b32_e32 v3, v219, v3, vcc
	v_lshlrev_b32_e32 v181, 2, v3
	v_xor_b32_e32 v3, 32, v219
	v_lshl_add_u64 v[150:151], v[134:135], 0, v[148:149]
	v_cmp_lt_i32_e32 vcc, v3, v140
	s_waitcnt vmcnt(11)
	v_mov_b64_e32 v[140:141], v[190:191]
	v_mov_b64_e32 v[142:143], v[192:193]
	global_load_dwordx4 v[190:193], v[246:247], off offset:16
	s_nop 0
	s_waitcnt vmcnt(11)
	v_mov_b64_e32 v[150:151], v[194:195]
	v_mov_b64_e32 v[152:153], v[196:197]
	global_load_dwordx4 v[194:197], v[246:247], off
	v_cndmask_b32_e32 v3, v219, v3, vcc
	v_lshlrev_b32_e32 v180, 2, v3
	v_readlane_b32 s70, v250, 30
	v_lshl_add_u32 v144, s22, 8, v166
	v_readlane_b32 s71, v250, 31
	v_ashrrev_i32_e32 v145, 31, v144
	s_lshl_b32 s0, s22, 3
	v_readlane_b32 s1, v252, 30
	s_or_b32 s60, s0, s1
	s_ashr_i32 s61, s60, 31
	s_waitcnt lgkmcnt(0)
	v_pk_add_f32 v[140:141], v[140:141], v[142:143]
	v_pk_add_f32 v[150:151], v[150:151], v[152:153]
	s_nop 0
	v_pk_add_f32 v[140:141], v[150:151], v[140:141]
	ds_bpermute_b32 v142, v181, v140
	ds_bpermute_b32 v143, v181, v141
	s_waitcnt lgkmcnt(0)
	v_pk_add_f32 v[140:141], v[140:141], v[142:143]
	ds_bpermute_b32 v142, v180, v140
	ds_bpermute_b32 v143, v180, v141
	s_waitcnt lgkmcnt(0)
	v_pk_add_f32 v[140:141], v[140:141], v[142:143]
	s_nop 0
	v_pk_mul_f32 v[160:161], v[140:141], s[82:83] op_sel_hi:[1,0]
	v_lshlrev_b64 v[140:141], 11, v[146:147]
	v_lshl_add_u64 v[140:141], s[70:71], 0, v[140:141]
	v_lshl_add_u64 v[152:153], v[144:145], 1, v[140:141]
	v_add_u32_e32 v243, 0x10000, v242
	s_waitcnt vmcnt(11)
	v_mov_b64_e32 v[140:141], v[198:199]
	global_load_dwordx2 v[198:199], v243, s[70:71]
	v_fma_f32 v3, -v160, v160, v161
	v_max_f32_e32 v3, 0, v3
	v_add_f32_e32 v3, 0x3727c5ac, v3
	v_rsq_f32_e32 v162, v3
	s_waitcnt lgkmcnt(0)
	v_lshlrev_b32_e32 v142, 16, v141
	v_and_b32_e32 v143, 0xffff0000, v141
	v_lshlrev_b32_e32 v3, 16, v140
	v_and_b32_e32 v140, 0xffff0000, v140
	v_sub_f32_e32 v143, v143, v160
	v_sub_f32_e32 v142, v142, v160
	v_sub_f32_e32 v141, v140, v160
	v_sub_f32_e32 v140, v3, v160
	v_pk_mul_f32 v[150:151], v[142:143], v[162:163] op_sel_hi:[1,0]
	v_lshlrev_b64 v[142:143], 2, v[144:145]
	v_pk_mul_f32 v[158:159], v[140:141], v[162:163] op_sel_hi:[1,0]
	v_lshl_add_u64 v[140:141], s[46:47], 0, v[142:143]
	v_lshl_add_u64 v[142:143], s[48:49], 0, v[142:143]
	ds_read_b128 v[154:157], v244
	ds_read_b128 v[182:185], v244 offset:256
	s_waitcnt lgkmcnt(0)
	v_pk_fma_f32 v[154:155], v[154:155], v[158:159], v[182:183]
	s_nop 0
	v_pk_fma_f32 v[128:129], v[154:155], s[72:73], v[128:129] op_sel_hi:[1,0,1]
	s_waitcnt vmcnt(11)
	v_mov_b64_e32 v[154:155], v[200:201]
	global_load_dwordx2 v[200:201], v243, s[70:71] offset:32
	v_pk_fma_f32 v[150:151], v[156:157], v[150:151], v[184:185]
	s_waitcnt lgkmcnt(0)
	v_lshlrev_b32_e32 v3, 16, v154
	v_pk_fma_f32 v[130:131], v[150:151], s[72:73], v[130:131] op_sel_hi:[1,0,1]
	v_cvt_pk_bf16_f32 v150, v128, v129
	v_cvt_pk_bf16_f32 v151, v130, v131
	v_and_b32_e32 v129, 0xffff0000, v154
	v_lshlrev_b32_e32 v131, 16, v155
	v_and_b32_e32 v147, 0xffff0000, v155
	global_store_dwordx2 v[152:153], v[150:151], off
	v_sub_f32_e32 v155, v129, v160
	v_sub_f32_e32 v154, v3, v160
	v_sub_f32_e32 v157, v147, v160
	v_sub_f32_e32 v156, v131, v160
	v_pk_mul_f32 v[158:159], v[162:163], v[156:157] op_sel_hi:[0,1]
	v_pk_mul_f32 v[168:169], v[162:163], v[154:155] op_sel_hi:[0,1]
	ds_read_b128 v[154:157], v244 offset:64
	ds_read_b128 v[182:185], v244 offset:320
	v_and_b32_e32 v130, 0xffff0000, v150
	v_lshlrev_b32_e32 v128, 16, v151
	s_waitcnt lgkmcnt(0)
; __device__ __forceinline__ u32x2 pk4(f32x4 v) { u32x2 r; r.x = pk2(v.x, v.y); r.y = pk2(v.z, v.w); return r; }
;     __device__ __forceinline__ void operator()(const f32x4 (&acc)[2][2][4][2], const pg8::Unit& u, int wr, int wc, int fr, int fq) const {
;     ...
;                 for (int bj = 0; bj < 2; ++bj)
; #pragma unroll
;                     for (int n = 0; n < 2; ++n) {
;                         const int col = u.pn * 256 + bj * 128 + wc * 32 + n * 16 + fq * 4;
;                         const u32x2 raw = *(const u32x2*)(src + (size_t)row * DM + col);
;                         f32x4 x = (f32x4){bflo(raw.x), bfhi(raw.x), bflo(raw.y), bfhi(raw.y)};
;                         if (ln) x = (x - mu) * rs * *(const f32x4*)(g + col) + *(const f32x4*)(b + col);
;                         const u32x2 pz = pk4(x * ALPHA + acc[ai][bj][m][n]);
;                         *(u32x2*)(dst + (size_t)row * DM + col) = pz;
;                         const float z0 = bflo(pz.x), z1 = bfhi(pz.x), z2 = bflo(pz.y), z3 = bfhi(pz.y);
;                         s1 += (z0 + z1) + (z2 + z3); s2 += (z0 * z0 + z1 * z1) + (z2 * z2 + z3 * z3);
;                     }
;                 s1 += __shfl_xor(s1, 16); s2 += __shfl_xor(s2, 16); s1 += __shfl_xor(s1, 32); s2 += __shfl_xor(s2, 32);
;                 if (fq == 0) { float* p = stm_n + (size_t)row * 32 + (u.pn * 4 + wc) * 2; p[0] = s1; p[1] = s2; }
	v_pk_fma_f32 v[154:155], v[154:155], v[168:169], v[182:183]
	s_nop 0
	v_pk_fma_f32 v[124:125], v[154:155], s[72:73], v[124:125] op_sel_hi:[1,0,1]
	s_waitcnt vmcnt(12)
	v_mov_b64_e32 v[154:155], v[202:203]
	global_load_dwordx2 v[202:203], v243, s[70:71] offset:256
	v_pk_fma_f32 v[156:157], v[156:157], v[158:159], v[184:185]
	v_cvt_pk_bf16_f32 v158, v124, v125
	v_pk_fma_f32 v[126:127], v[156:157], s[72:73], v[126:127] op_sel_hi:[1,0,1]
	s_waitcnt lgkmcnt(0)
	v_lshlrev_b32_e32 v3, 16, v154
	v_cvt_pk_bf16_f32 v159, v126, v127
	v_lshlrev_b32_e32 v126, 16, v159
	v_and_b32_e32 v127, 0xffff0000, v159
	v_mul_f32_e32 v124, v126, v126
	v_pk_fma_f32 v[124:125], v[126:127], v[126:127], v[124:125] op_sel_hi:[1,1,0]
	v_lshlrev_b32_e32 v129, 16, v155
	v_and_b32_e32 v124, 0xffff0000, v154
	v_and_b32_e32 v131, 0xffff0000, v155
	global_store_dwordx2 v[152:153], v[158:159], off offset:32
	v_sub_f32_e32 v155, v124, v160
	v_sub_f32_e32 v154, v3, v160
	v_sub_f32_e32 v157, v131, v160
	v_sub_f32_e32 v156, v129, v160
	v_pk_mul_f32 v[168:169], v[162:163], v[156:157] op_sel_hi:[0,1]
	v_pk_mul_f32 v[186:187], v[162:163], v[154:155] op_sel_hi:[0,1]
	ds_read_b128 v[154:157], v244 offset:128
	ds_read_b128 v[182:185], v244 offset:384
	v_and_b32_e32 v159, 0xffff0000, v158
	s_waitcnt lgkmcnt(0)
	v_pk_fma_f32 v[154:155], v[154:155], v[186:187], v[182:183]
	v_pk_fma_f32 v[156:157], v[156:157], v[168:169], v[184:185]
	v_pk_fma_f32 v[120:121], v[154:155], s[72:73], v[120:121] op_sel_hi:[1,0,1]
	v_pk_fma_f32 v[122:123], v[156:157], s[72:73], v[122:123] op_sel_hi:[1,0,1]
	s_waitcnt vmcnt(13)
	v_mov_b64_e32 v[168:169], v[204:205]
	global_load_dwordx2 v[204:205], v243, s[70:71] offset:288
	v_cvt_pk_bf16_f32 v120, v120, v121
	v_cvt_pk_bf16_f32 v121, v122, v123
	global_store_dwordx2 v[152:153], v[120:121], off offset:256
	ds_read_b128 v[182:185], v244 offset:192
	ds_read_b128 v[186:189], v244 offset:448
	v_lshlrev_b32_e32 v154, 16, v120
	v_and_b32_e32 v156, 0xffff0000, v120
	v_lshlrev_b32_e32 v120, 16, v121
	v_and_b32_e32 v122, 0xffff0000, v121
	v_mul_f32_e32 v155, v154, v154
	v_mul_f32_e32 v157, v156, v156
	v_mul_f32_e32 v121, v120, v120
	v_mul_f32_e32 v123, v122, v122
	v_pk_add_f32 v[120:121], v[120:121], v[122:123]
	s_waitcnt lgkmcnt(0)
	v_lshlrev_b32_e32 v3, 16, v168
	v_and_b32_e32 v124, 0xffff0000, v168
	v_lshlrev_b32_e32 v129, 16, v169
	v_and_b32_e32 v131, 0xffff0000, v169
	v_sub_f32_e32 v169, v124, v160
	v_sub_f32_e32 v168, v3, v160
	v_sub_f32_e32 v161, v131, v160
	v_sub_f32_e32 v160, v129, v160
	v_pk_mul_f32 v[160:161], v[162:163], v[160:161] op_sel_hi:[0,1]
	v_pk_mul_f32 v[162:163], v[162:163], v[168:169] op_sel_hi:[0,1]
	s_waitcnt lgkmcnt(0)
	v_pk_fma_f32 v[162:163], v[182:183], v[162:163], v[186:187]
	v_mov_b32_e32 v129, v159
	v_pk_fma_f32 v[116:117], v[162:163], s[72:73], v[116:117] op_sel_hi:[1,0,1]
	v_lshlrev_b32_e32 v163, 16, v158
	v_lshlrev_b32_e32 v162, 16, v150
	v_mov_b32_e32 v131, v163
	v_pk_mul_f32 v[168:169], v[162:163], v[162:163]
	v_pk_mul_f32 v[182:183], v[130:131], v[130:131]
	v_and_b32_e32 v158, 0xffff0000, v151
	v_pk_fma_f32 v[160:161], v[184:185], v[160:161], v[188:189]
	v_pk_mul_f32 v[150:151], v[128:129], v[128:129]
	v_pk_mul_f32 v[184:185], v[158:159], v[158:159]
	v_pk_mov_b32 v[186:187], v[162:163], v[168:169] op_sel:[1,0]
	v_pk_mov_b32 v[182:183], v[158:159], v[182:183] op_sel:[1,0]
	v_pk_add_f32 v[130:131], v[162:163], v[130:131]
	v_pk_add_f32 v[128:129], v[158:159], v[128:129]
	v_pk_fma_f32 v[118:119], v[160:161], s[72:73], v[118:119] op_sel_hi:[1,0,1]
	v_pk_add_f32 v[182:183], v[186:187], v[182:183]
	v_mov_b32_e32 v186, v126
	v_mov_b32_e32 v187, v150
	v_pk_mov_b32 v[126:127], v[126:127], v[184:185] op_sel:[1,0]
	v_mov_b32_e32 v131, v169
	v_mov_b32_e32 v129, v185
	v_cvt_pk_bf16_f32 v116, v116, v117
	v_cvt_pk_bf16_f32 v117, v118, v119
	v_pk_add_f32 v[126:127], v[186:187], v[126:127]
	v_pk_add_f32 v[128:129], v[130:131], v[128:129]
	v_mov_b32_e32 v3, v125
	global_store_dwordx2 v[152:153], v[116:117], off offset:288
	v_lshlrev_b32_e32 v152, 16, v116
	v_and_b32_e32 v160, 0xffff0000, v116
	v_lshlrev_b32_e32 v116, 16, v117
	v_and_b32_e32 v118, 0xffff0000, v117
	v_pk_add_f32 v[126:127], v[182:183], v[126:127]
	v_pk_add_f32 v[124:125], v[128:129], v[2:3]
	v_mul_f32_e32 v153, v152, v152
	v_mul_f32_e32 v161, v160, v160
	v_mul_f32_e32 v117, v116, v116
	v_mul_f32_e32 v119, v118, v118
	v_pk_add_f32 v[124:125], v[126:127], v[124:125]
	v_pk_add_f32 v[126:127], v[154:155], v[156:157]
	v_pk_add_f32 v[122:123], v[152:153], v[160:161]
	v_pk_add_f32 v[120:121], v[126:127], v[120:121]
	v_pk_add_f32 v[116:117], v[116:117], v[118:119]
	v_pk_add_f32 v[120:121], v[124:125], v[120:121]
	v_pk_add_f32 v[116:117], v[122:123], v[116:117]
	s_nop 0
	v_pk_add_f32 v[116:117], v[120:121], v[116:117]
	ds_bpermute_b32 v118, v181, v116
	ds_bpermute_b32 v119, v181, v117
	s_waitcnt lgkmcnt(0)
	v_pk_add_f32 v[116:117], v[116:117], v[118:119]
	ds_bpermute_b32 v118, v180, v116
	ds_bpermute_b32 v119, v180, v117
	s_and_saveexec_b64 s[0:1], s[40:41]
	s_cbranch_execz .LBB0_2205
	v_lshl_add_u64 v[120:121], s[50:51], 0, v[148:149]
	v_lshl_add_u64 v[120:121], s[60:61], 2, v[120:121]
	s_waitcnt lgkmcnt(0)
	v_pk_add_f32 v[116:117], v[116:117], v[118:119]
	global_store_dwordx2 v[120:121], v[116:117], off
; __device__ __forceinline__ u32x2 pk4(f32x4 v) { u32x2 r; r.x = pk2(v.x, v.y); r.y = pk2(v.z, v.w); return r; }
; __device__ __forceinline__ void stats_main(const float* stm, int row, int fq, float& mu, float& rs) {
;     const f32x4* p = (const f32x4*)(stm + (size_t)row * 32 + fq * 8);
;     const f32x4 a = p[0], b = p[1];
;     float s1 = (a.x + a.z) + (b.x + b.z), s2 = (a.y + a.w) + (b.y + b.w);
;     s1 += __shfl_xor(s1, 16); s2 += __shfl_xor(s2, 16); s1 += __shfl_xor(s1, 32); s2 += __shfl_xor(s2, 32);
;     mu = s1 * (1.f / DM); rs = __builtin_amdgcn_rsqf(fmaxf(s2 * (1.f / DM) - mu * mu, 0.f) + LN_EPS);
; }
;     __device__ __forceinline__ void operator()(const f32x4 (&acc)[2][2][4][2], const pg8::Unit& u, int wr, int wc, int fr, int fq) const {
;     ...
;                 for (int bj = 0; bj < 2; ++bj)
; #pragma unroll
;                     for (int n = 0; n < 2; ++n) {
;                         const int col = u.pn * 256 + bj * 128 + wc * 32 + n * 16 + fq * 4;
;                         const u32x2 raw = *(const u32x2*)(src + (size_t)row * DM + col);
;                         f32x4 x = (f32x4){bflo(raw.x), bfhi(raw.x), bflo(raw.y), bfhi(raw.y)};
;                         if (ln) x = (x - mu) * rs * *(const f32x4*)(g + col) + *(const f32x4*)(b + col);
;                         const u32x2 pz = pk4(x * ALPHA + acc[ai][bj][m][n]);
;                         *(u32x2*)(dst + (size_t)row * DM + col) = pz;
;                         const float z0 = bflo(pz.x), z1 = bfhi(pz.x), z2 = bflo(pz.y), z3 = bfhi(pz.y);
;                         s1 += (z0 + z1) + (z2 + z3); s2 += (z0 * z0 + z1 * z1) + (z2 * z2 + z3 * z3);
;                     }
.LBB0_2205:
	s_or_b64 exec, exec, s[0:1]
	v_or_b32_e32 v126, 16, v146
	v_ashrrev_i32_e32 v127, 31, v126
	v_lshlrev_b64 v[116:117], 7, v[126:127]
	v_lshl_add_u64 v[122:123], v[134:135], 0, v[116:117]
	s_waitcnt lgkmcnt(0)
	s_waitcnt vmcnt(16)
	v_mov_b64_e32 v[118:119], v[206:207]
	v_mov_b64_e32 v[120:121], v[208:209]
	global_load_dwordx4 v[206:209], v[246:247], off offset:2064
	s_nop 0
	s_waitcnt vmcnt(16)
	v_mov_b64_e32 v[122:123], v[214:215]
	v_mov_b64_e32 v[124:125], v[216:217]
	global_load_dwordx4 v[214:217], v[246:247], off offset:2048
	s_waitcnt lgkmcnt(0)
	v_pk_add_f32 v[118:119], v[118:119], v[120:121]
	s_waitcnt lgkmcnt(0)
	v_pk_add_f32 v[122:123], v[122:123], v[124:125]
	s_nop 0
	v_pk_add_f32 v[118:119], v[122:123], v[118:119]
	ds_bpermute_b32 v120, v181, v118
	ds_bpermute_b32 v121, v181, v119
	s_waitcnt lgkmcnt(0)
	v_pk_add_f32 v[118:119], v[118:119], v[120:121]
	ds_bpermute_b32 v120, v180, v118
	ds_bpermute_b32 v121, v180, v119
	s_waitcnt lgkmcnt(0)
	v_pk_add_f32 v[118:119], v[118:119], v[120:121]
	s_nop 0
	v_pk_mul_f32 v[128:129], v[118:119], s[82:83] op_sel_hi:[1,0]
	v_lshlrev_b64 v[118:119], 11, v[126:127]
	v_lshl_add_u64 v[118:119], s[70:71], 0, v[118:119]
	v_lshl_add_u64 v[124:125], v[144:145], 1, v[118:119]
	v_add_u32_e32 v243, 0x18000, v242
	s_waitcnt vmcnt(16)
	v_mov_b64_e32 v[118:119], v[234:235]
	global_load_dwordx2 v[234:235], v243, s[70:71]
	v_fma_f32 v3, -v128, v128, v129
	v_max_f32_e32 v3, 0, v3
	v_add_f32_e32 v3, 0x3727c5ac, v3
	v_rsq_f32_e32 v130, v3
	s_waitcnt lgkmcnt(0)
	v_lshlrev_b32_e32 v3, 16, v118
	v_and_b32_e32 v118, 0xffff0000, v118
	v_lshlrev_b32_e32 v120, 16, v119
	v_and_b32_e32 v121, 0xffff0000, v119
	v_sub_f32_e32 v119, v118, v128
	v_sub_f32_e32 v118, v3, v128
	v_sub_f32_e32 v121, v121, v128
	v_sub_f32_e32 v120, v120, v128
	v_pk_mul_f32 v[122:123], v[120:121], v[130:131] op_sel_hi:[1,0]
	v_pk_mul_f32 v[126:127], v[118:119], v[130:131] op_sel_hi:[1,0]
	ds_read_b128 v[118:121], v244
	ds_read_b128 v[148:151], v244 offset:256
	s_waitcnt lgkmcnt(0)
	v_pk_fma_f32 v[120:121], v[120:121], v[122:123], v[150:151]
	s_nop 0
	v_pk_fma_f32 v[114:115], v[120:121], s[72:73], v[114:115] op_sel_hi:[1,0,1]
	s_waitcnt vmcnt(16)
	v_mov_b64_e32 v[120:121], v[236:237]
	global_load_dwordx2 v[236:237], v243, s[70:71] offset:32
	v_pk_fma_f32 v[118:119], v[118:119], v[126:127], v[148:149]
	s_waitcnt lgkmcnt(0)
	v_lshlrev_b32_e32 v3, 16, v120
	v_pk_fma_f32 v[112:113], v[118:119], s[72:73], v[112:113] op_sel_hi:[1,0,1]
	v_cvt_pk_bf16_f32 v119, v114, v115
	v_cvt_pk_bf16_f32 v118, v112, v113
	v_and_b32_e32 v113, 0xffff0000, v120
	v_lshlrev_b32_e32 v115, 16, v121
	v_and_b32_e32 v122, 0xffff0000, v121
	global_store_dwordx2 v[124:125], v[118:119], off
	v_sub_f32_e32 v121, v113, v128
	v_sub_f32_e32 v120, v3, v128
	v_sub_f32_e32 v123, v122, v128
	v_sub_f32_e32 v122, v115, v128
	v_pk_mul_f32 v[126:127], v[130:131], v[122:123] op_sel_hi:[0,1]
	v_pk_mul_f32 v[152:153], v[130:131], v[120:121] op_sel_hi:[0,1]
	ds_read_b128 v[120:123], v244 offset:64
	ds_read_b128 v[148:151], v244 offset:320
	v_and_b32_e32 v114, 0xffff0000, v118
	v_lshlrev_b32_e32 v112, 16, v119
	s_waitcnt lgkmcnt(0)
	v_pk_fma_f32 v[120:121], v[120:121], v[152:153], v[148:149]
	s_nop 0
	v_pk_fma_f32 v[108:109], v[120:121], s[72:73], v[108:109] op_sel_hi:[1,0,1]
	s_waitcnt vmcnt(17)
	v_mov_b64_e32 v[120:121], v[238:239]
	global_load_dwordx2 v[238:239], v243, s[70:71] offset:256
	v_pk_fma_f32 v[122:123], v[122:123], v[126:127], v[150:151]
	v_cvt_pk_bf16_f32 v126, v108, v109
	v_pk_fma_f32 v[110:111], v[122:123], s[72:73], v[110:111] op_sel_hi:[1,0,1]
	s_waitcnt lgkmcnt(0)
	v_lshlrev_b32_e32 v3, 16, v120
	v_cvt_pk_bf16_f32 v127, v110, v111
	v_lshlrev_b32_e32 v110, 16, v127
	v_and_b32_e32 v111, 0xffff0000, v127
	v_mul_f32_e32 v108, v110, v110
	v_pk_fma_f32 v[108:109], v[110:111], v[110:111], v[108:109] op_sel_hi:[1,1,0]
	v_lshlrev_b32_e32 v113, 16, v121
	v_and_b32_e32 v108, 0xffff0000, v120
	v_and_b32_e32 v115, 0xffff0000, v121
	global_store_dwordx2 v[124:125], v[126:127], off offset:32
	v_sub_f32_e32 v121, v108, v128
	v_sub_f32_e32 v120, v3, v128
	v_sub_f32_e32 v123, v115, v128
	v_sub_f32_e32 v122, v113, v128
	v_pk_mul_f32 v[152:153], v[130:131], v[122:123] op_sel_hi:[0,1]
	v_pk_mul_f32 v[154:155], v[130:131], v[120:121] op_sel_hi:[0,1]
	ds_read_b128 v[120:123], v244 offset:128
	ds_read_b128 v[148:151], v244 offset:384
	v_and_b32_e32 v127, 0xffff0000, v126
	s_waitcnt lgkmcnt(0)
	v_pk_fma_f32 v[120:121], v[120:121], v[154:155], v[148:149]
	s_waitcnt vmcnt(18)
	v_mov_b64_e32 v[148:149], v[240:241]
	global_load_dwordx2 v[240:241], v243, s[70:71] offset:288
	v_pk_fma_f32 v[122:123], v[122:123], v[152:153], v[150:151]
	v_pk_fma_f32 v[104:105], v[120:121], s[72:73], v[104:105] op_sel_hi:[1,0,1]
	v_pk_fma_f32 v[106:107], v[122:123], s[72:73], v[106:107] op_sel_hi:[1,0,1]
	v_cvt_pk_bf16_f32 v104, v104, v105
	v_cvt_pk_bf16_f32 v105, v106, v107
	global_store_dwordx2 v[124:125], v[104:105], off offset:256
	v_lshlrev_b32_e32 v120, 16, v104
	v_and_b32_e32 v122, 0xffff0000, v104
	v_lshlrev_b32_e32 v104, 16, v105
	v_and_b32_e32 v106, 0xffff0000, v105
	v_mul_f32_e32 v121, v120, v120
	v_mul_f32_e32 v123, v122, v122
	v_mul_f32_e32 v105, v104, v104
	v_mul_f32_e32 v107, v106, v106
	v_pk_add_f32 v[104:105], v[104:105], v[106:107]
	s_waitcnt lgkmcnt(0)
	v_lshlrev_b32_e32 v3, 16, v148
	v_and_b32_e32 v108, 0xffff0000, v148
	v_lshlrev_b32_e32 v113, 16, v149
	v_and_b32_e32 v115, 0xffff0000, v149
	v_sub_f32_e32 v149, v108, v128
	v_sub_f32_e32 v148, v3, v128
	v_sub_f32_e32 v129, v115, v128
	v_sub_f32_e32 v128, v113, v128
	v_pk_mul_f32 v[128:129], v[130:131], v[128:129] op_sel_hi:[0,1]
	v_pk_mul_f32 v[130:131], v[130:131], v[148:149] op_sel_hi:[0,1]
	ds_read_b128 v[148:151], v244 offset:192
	ds_read_b128 v[152:155], v244 offset:448
	v_mov_b32_e32 v113, v127
	v_mov_b32_e32 v3, v109
	s_waitcnt lgkmcnt(0)
; __device__ __forceinline__ u32x2 pk4(f32x4 v) { u32x2 r; r.x = pk2(v.x, v.y); r.y = pk2(v.z, v.w); return r; }
; __device__ __forceinline__ void stats_main(const float* stm, int row, int fq, float& mu, float& rs) {
;     const f32x4* p = (const f32x4*)(stm + (size_t)row * 32 + fq * 8);
;     const f32x4 a = p[0], b = p[1];
;     float s1 = (a.x + a.z) + (b.x + b.z), s2 = (a.y + a.w) + (b.y + b.w);
;     s1 += __shfl_xor(s1, 16); s2 += __shfl_xor(s2, 16); s1 += __shfl_xor(s1, 32); s2 += __shfl_xor(s2, 32);
;     mu = s1 * (1.f / DM); rs = __builtin_amdgcn_rsqf(fmaxf(s2 * (1.f / DM) - mu * mu, 0.f) + LN_EPS);
; }
;     __device__ __forceinline__ void operator()(const f32x4 (&acc)[2][2][4][2], const pg8::Unit& u, int wr, int wc, int fr, int fq) const {
;     ...
;                         f32x4 x = (f32x4){bflo(raw.x), bfhi(raw.x), bflo(raw.y), bfhi(raw.y)};
;                         if (ln) x = (x - mu) * rs * *(const f32x4*)(g + col) + *(const f32x4*)(b + col);
;                         const u32x2 pz = pk4(x * ALPHA + acc[ai][bj][m][n]);
;                         *(u32x2*)(dst + (size_t)row * DM + col) = pz;
;                         const float z0 = bflo(pz.x), z1 = bfhi(pz.x), z2 = bflo(pz.y), z3 = bfhi(pz.y);
;                         s1 += (z0 + z1) + (z2 + z3); s2 += (z0 * z0 + z1 * z1) + (z2 * z2 + z3 * z3);
;                     }
;                 s1 += __shfl_xor(s1, 16); s2 += __shfl_xor(s2, 16); s1 += __shfl_xor(s1, 32); s2 += __shfl_xor(s2, 32);
;                 if (fq == 0) { float* p = stm_n + (size_t)row * 32 + (u.pn * 4 + wc) * 2; p[0] = s1; p[1] = s2; }
	v_pk_fma_f32 v[130:131], v[148:149], v[130:131], v[152:153]
	s_nop 0
	v_pk_fma_f32 v[100:101], v[130:131], s[72:73], v[100:101] op_sel_hi:[1,0,1]
	v_lshlrev_b32_e32 v131, 16, v126
	v_lshlrev_b32_e32 v130, 16, v118
	v_mov_b32_e32 v115, v131
	v_pk_fma_f32 v[128:129], v[150:151], v[128:129], v[154:155]
	v_pk_mul_f32 v[148:149], v[130:131], v[130:131]
	v_pk_mul_f32 v[150:151], v[114:115], v[114:115]
	v_and_b32_e32 v126, 0xffff0000, v119
	v_pk_mul_f32 v[118:119], v[112:113], v[112:113]
	v_pk_mul_f32 v[152:153], v[126:127], v[126:127]
	v_pk_mov_b32 v[154:155], v[130:131], v[148:149] op_sel:[1,0]
	v_pk_mov_b32 v[150:151], v[126:127], v[150:151] op_sel:[1,0]
	v_pk_add_f32 v[114:115], v[130:131], v[114:115]
	v_pk_add_f32 v[112:113], v[126:127], v[112:113]
	v_pk_fma_f32 v[102:103], v[128:129], s[72:73], v[102:103] op_sel_hi:[1,0,1]
	v_pk_add_f32 v[150:151], v[154:155], v[150:151]
	v_mov_b32_e32 v154, v110
	v_mov_b32_e32 v155, v118
	v_pk_mov_b32 v[110:111], v[110:111], v[152:153] op_sel:[1,0]
	v_mov_b32_e32 v115, v149
	v_mov_b32_e32 v113, v153
	v_cvt_pk_bf16_f32 v100, v100, v101
	v_cvt_pk_bf16_f32 v101, v102, v103
	v_pk_add_f32 v[110:111], v[154:155], v[110:111]
	v_pk_add_f32 v[112:113], v[114:115], v[112:113]
	global_store_dwordx2 v[124:125], v[100:101], off offset:288
	v_lshlrev_b32_e32 v124, 16, v100
	v_and_b32_e32 v128, 0xffff0000, v100
	v_lshlrev_b32_e32 v100, 16, v101
	v_and_b32_e32 v102, 0xffff0000, v101
	v_pk_add_f32 v[110:111], v[150:151], v[110:111]
	v_pk_add_f32 v[108:109], v[112:113], v[2:3]
	v_mul_f32_e32 v125, v124, v124
	v_mul_f32_e32 v129, v128, v128
	v_mul_f32_e32 v101, v100, v100
	v_mul_f32_e32 v103, v102, v102
	v_pk_add_f32 v[108:109], v[110:111], v[108:109]
	v_pk_add_f32 v[110:111], v[120:121], v[122:123]
	v_pk_add_f32 v[106:107], v[124:125], v[128:129]
	v_pk_add_f32 v[104:105], v[110:111], v[104:105]
	v_pk_add_f32 v[100:101], v[100:101], v[102:103]
	v_pk_add_f32 v[104:105], v[108:109], v[104:105]
	v_pk_add_f32 v[100:101], v[106:107], v[100:101]
	s_nop 0
	v_pk_add_f32 v[100:101], v[104:105], v[100:101]
	ds_bpermute_b32 v102, v181, v100
	ds_bpermute_b32 v103, v181, v101
	s_waitcnt lgkmcnt(0)
	v_pk_add_f32 v[100:101], v[100:101], v[102:103]
	ds_bpermute_b32 v102, v180, v100
	ds_bpermute_b32 v103, v180, v101
	s_and_saveexec_b64 s[0:1], s[40:41]
	s_cbranch_execz .LBB0_2207
	v_lshl_add_u64 v[104:105], s[50:51], 0, v[116:117]
	v_lshl_add_u64 v[104:105], s[60:61], 2, v[104:105]
	s_waitcnt lgkmcnt(0)
	v_pk_add_f32 v[100:101], v[100:101], v[102:103]
	global_store_dwordx2 v[104:105], v[100:101], off
.LBB0_2207:
	s_or_b64 exec, exec, s[0:1]
	v_or_b32_e32 v110, 32, v146
	v_ashrrev_i32_e32 v111, 31, v110
	v_lshlrev_b64 v[100:101], 7, v[110:111]
	v_lshl_add_u64 v[106:107], v[134:135], 0, v[100:101]
	s_waitcnt lgkmcnt(0)
	s_waitcnt vmcnt(21)
	v_mov_b64_e32 v[102:103], v[190:191]
	v_mov_b64_e32 v[104:105], v[192:193]
	global_load_dwordx4 v[190:193], v[248:249], off offset:-4080
	s_nop 0
	s_waitcnt vmcnt(21)
	v_mov_b64_e32 v[106:107], v[194:195]
	v_mov_b64_e32 v[108:109], v[196:197]
	global_load_dwordx4 v[194:197], v[248:249], off offset:-4096
	s_waitcnt lgkmcnt(0)
	v_pk_add_f32 v[102:103], v[102:103], v[104:105]
	s_waitcnt lgkmcnt(0)
	v_pk_add_f32 v[106:107], v[106:107], v[108:109]
	s_nop 0
	v_pk_add_f32 v[102:103], v[106:107], v[102:103]
	ds_bpermute_b32 v104, v181, v102
	ds_bpermute_b32 v105, v181, v103
	s_waitcnt lgkmcnt(0)
	v_pk_add_f32 v[102:103], v[102:103], v[104:105]
	ds_bpermute_b32 v104, v180, v102
	ds_bpermute_b32 v105, v180, v103
	s_waitcnt lgkmcnt(0)
	v_pk_add_f32 v[102:103], v[102:103], v[104:105]
	s_nop 0
	v_pk_mul_f32 v[112:113], v[102:103], s[82:83] op_sel_hi:[1,0]
	v_lshlrev_b64 v[102:103], 11, v[110:111]
	v_lshl_add_u64 v[102:103], s[70:71], 0, v[102:103]
	v_lshl_add_u64 v[108:109], v[144:145], 1, v[102:103]
	v_add_u32_e32 v243, 0x40000, v242
	s_waitcnt vmcnt(21)
	v_mov_b64_e32 v[102:103], v[198:199]
	global_load_dwordx2 v[198:199], v243, s[70:71]
	v_fma_f32 v3, -v112, v112, v113
	v_max_f32_e32 v3, 0, v3
	v_add_f32_e32 v3, 0x3727c5ac, v3
	v_rsq_f32_e32 v114, v3
	s_waitcnt lgkmcnt(0)
	v_lshlrev_b32_e32 v3, 16, v102
	v_and_b32_e32 v102, 0xffff0000, v102
	v_lshlrev_b32_e32 v104, 16, v103
	v_and_b32_e32 v105, 0xffff0000, v103
	v_sub_f32_e32 v103, v102, v112
	v_sub_f32_e32 v102, v3, v112
	v_sub_f32_e32 v105, v105, v112
	v_sub_f32_e32 v104, v104, v112
	v_pk_mul_f32 v[106:107], v[104:105], v[114:115] op_sel_hi:[1,0]
	v_pk_mul_f32 v[110:111], v[102:103], v[114:115] op_sel_hi:[1,0]
	ds_read_b128 v[102:105], v244
	ds_read_b128 v[116:119], v244 offset:256
	s_waitcnt lgkmcnt(0)
	v_pk_fma_f32 v[104:105], v[104:105], v[106:107], v[118:119]
	s_nop 0
	v_pk_fma_f32 v[98:99], v[104:105], s[72:73], v[98:99] op_sel_hi:[1,0,1]
	s_waitcnt vmcnt(21)
	v_mov_b64_e32 v[104:105], v[200:201]
	global_load_dwordx2 v[200:201], v243, s[70:71] offset:32
	v_pk_fma_f32 v[102:103], v[102:103], v[110:111], v[116:117]
	s_waitcnt lgkmcnt(0)
	v_lshlrev_b32_e32 v3, 16, v104
	v_pk_fma_f32 v[96:97], v[102:103], s[72:73], v[96:97] op_sel_hi:[1,0,1]
	v_cvt_pk_bf16_f32 v103, v98, v99
	v_cvt_pk_bf16_f32 v102, v96, v97
	v_and_b32_e32 v97, 0xffff0000, v104
	v_lshlrev_b32_e32 v99, 16, v105
	v_and_b32_e32 v106, 0xffff0000, v105
	global_store_dwordx2 v[108:109], v[102:103], off
	v_sub_f32_e32 v105, v97, v112
	v_sub_f32_e32 v104, v3, v112
	v_sub_f32_e32 v107, v106, v112
	v_sub_f32_e32 v106, v99, v112
	v_pk_mul_f32 v[110:111], v[114:115], v[106:107] op_sel_hi:[0,1]
	v_pk_mul_f32 v[120:121], v[114:115], v[104:105] op_sel_hi:[0,1]
	ds_read_b128 v[104:107], v244 offset:64
	ds_read_b128 v[116:119], v244 offset:320
	v_and_b32_e32 v98, 0xffff0000, v102
	v_lshlrev_b32_e32 v96, 16, v103
	s_waitcnt lgkmcnt(0)
; __device__ __forceinline__ u32x2 pk4(f32x4 v) { u32x2 r; r.x = pk2(v.x, v.y); r.y = pk2(v.z, v.w); return r; }
;     __device__ __forceinline__ void operator()(const f32x4 (&acc)[2][2][4][2], const pg8::Unit& u, int wr, int wc, int fr, int fq) const {
;     ...
;                 for (int bj = 0; bj < 2; ++bj)
; #pragma unroll
;                     for (int n = 0; n < 2; ++n) {
;                         const int col = u.pn * 256 + bj * 128 + wc * 32 + n * 16 + fq * 4;
;                         const u32x2 raw = *(const u32x2*)(src + (size_t)row * DM + col);
;                         f32x4 x = (f32x4){bflo(raw.x), bfhi(raw.x), bflo(raw.y), bfhi(raw.y)};
;                         if (ln) x = (x - mu) * rs * *(const f32x4*)(g + col) + *(const f32x4*)(b + col);
;                         const u32x2 pz = pk4(x * ALPHA + acc[ai][bj][m][n]);
;                         *(u32x2*)(dst + (size_t)row * DM + col) = pz;
;                         const float z0 = bflo(pz.x), z1 = bfhi(pz.x), z2 = bflo(pz.y), z3 = bfhi(pz.y);
;                         s1 += (z0 + z1) + (z2 + z3); s2 += (z0 * z0 + z1 * z1) + (z2 * z2 + z3 * z3);
;                     }
;                 s1 += __shfl_xor(s1, 16); s2 += __shfl_xor(s2, 16); s1 += __shfl_xor(s1, 32); s2 += __shfl_xor(s2, 32);
;                 if (fq == 0) { float* p = stm_n + (size_t)row * 32 + (u.pn * 4 + wc) * 2; p[0] = s1; p[1] = s2; }
	v_pk_fma_f32 v[104:105], v[104:105], v[120:121], v[116:117]
	s_nop 0
	v_pk_fma_f32 v[92:93], v[104:105], s[72:73], v[92:93] op_sel_hi:[1,0,1]
	s_waitcnt vmcnt(21)
	v_mov_b64_e32 v[104:105], v[202:203]
	global_load_dwordx2 v[202:203], v243, s[70:71] offset:256
	v_pk_fma_f32 v[106:107], v[106:107], v[110:111], v[118:119]
	v_cvt_pk_bf16_f32 v110, v92, v93
	v_pk_fma_f32 v[94:95], v[106:107], s[72:73], v[94:95] op_sel_hi:[1,0,1]
	s_waitcnt lgkmcnt(0)
	v_lshlrev_b32_e32 v3, 16, v104
	v_cvt_pk_bf16_f32 v111, v94, v95
	v_lshlrev_b32_e32 v94, 16, v111
	v_and_b32_e32 v95, 0xffff0000, v111
	v_mul_f32_e32 v92, v94, v94
	v_pk_fma_f32 v[92:93], v[94:95], v[94:95], v[92:93] op_sel_hi:[1,1,0]
	v_lshlrev_b32_e32 v97, 16, v105
	v_and_b32_e32 v92, 0xffff0000, v104
	v_and_b32_e32 v99, 0xffff0000, v105
	global_store_dwordx2 v[108:109], v[110:111], off offset:32
	v_sub_f32_e32 v105, v92, v112
	v_sub_f32_e32 v104, v3, v112
	v_sub_f32_e32 v107, v99, v112
	v_sub_f32_e32 v106, v97, v112
	v_pk_mul_f32 v[120:121], v[114:115], v[106:107] op_sel_hi:[0,1]
	v_pk_mul_f32 v[122:123], v[114:115], v[104:105] op_sel_hi:[0,1]
	ds_read_b128 v[104:107], v244 offset:128
	ds_read_b128 v[116:119], v244 offset:384
	v_and_b32_e32 v111, 0xffff0000, v110
	s_waitcnt lgkmcnt(0)
	v_pk_fma_f32 v[104:105], v[104:105], v[122:123], v[116:117]
	s_waitcnt vmcnt(21)
	v_mov_b64_e32 v[116:117], v[204:205]
	global_load_dwordx2 v[204:205], v243, s[70:71] offset:288
	v_pk_fma_f32 v[106:107], v[106:107], v[120:121], v[118:119]
	v_pk_fma_f32 v[88:89], v[104:105], s[72:73], v[88:89] op_sel_hi:[1,0,1]
	v_pk_fma_f32 v[90:91], v[106:107], s[72:73], v[90:91] op_sel_hi:[1,0,1]
	v_cvt_pk_bf16_f32 v88, v88, v89
	v_cvt_pk_bf16_f32 v89, v90, v91
	global_store_dwordx2 v[108:109], v[88:89], off offset:256
	v_lshlrev_b32_e32 v104, 16, v88
	v_and_b32_e32 v106, 0xffff0000, v88
	v_lshlrev_b32_e32 v88, 16, v89
	v_and_b32_e32 v90, 0xffff0000, v89
	v_mul_f32_e32 v105, v104, v104
	v_mul_f32_e32 v107, v106, v106
	v_mul_f32_e32 v89, v88, v88
	v_mul_f32_e32 v91, v90, v90
	v_pk_add_f32 v[88:89], v[88:89], v[90:91]
	s_waitcnt lgkmcnt(0)
	v_lshlrev_b32_e32 v3, 16, v116
	v_and_b32_e32 v92, 0xffff0000, v116
	v_lshlrev_b32_e32 v97, 16, v117
	v_and_b32_e32 v99, 0xffff0000, v117
	v_sub_f32_e32 v117, v92, v112
	v_sub_f32_e32 v116, v3, v112
	v_sub_f32_e32 v113, v99, v112
	v_sub_f32_e32 v112, v97, v112
	v_pk_mul_f32 v[112:113], v[114:115], v[112:113] op_sel_hi:[0,1]
	v_pk_mul_f32 v[114:115], v[114:115], v[116:117] op_sel_hi:[0,1]
	ds_read_b128 v[116:119], v244 offset:192
	ds_read_b128 v[120:123], v244 offset:448
	v_mov_b32_e32 v97, v111
	v_mov_b32_e32 v3, v93
	s_waitcnt lgkmcnt(0)
	v_pk_fma_f32 v[114:115], v[116:117], v[114:115], v[120:121]
	s_nop 0
	v_pk_fma_f32 v[84:85], v[114:115], s[72:73], v[84:85] op_sel_hi:[1,0,1]
	v_lshlrev_b32_e32 v115, 16, v110
	v_lshlrev_b32_e32 v114, 16, v102
	v_mov_b32_e32 v99, v115
	v_pk_fma_f32 v[112:113], v[118:119], v[112:113], v[122:123]
	v_pk_mul_f32 v[116:117], v[114:115], v[114:115]
	v_pk_mul_f32 v[118:119], v[98:99], v[98:99]
	v_and_b32_e32 v110, 0xffff0000, v103
	v_pk_mul_f32 v[102:103], v[96:97], v[96:97]
	v_pk_mul_f32 v[120:121], v[110:111], v[110:111]
	v_pk_mov_b32 v[122:123], v[114:115], v[116:117] op_sel:[1,0]
	v_pk_mov_b32 v[118:119], v[110:111], v[118:119] op_sel:[1,0]
	v_pk_add_f32 v[98:99], v[114:115], v[98:99]
	v_pk_add_f32 v[96:97], v[110:111], v[96:97]
	v_pk_fma_f32 v[86:87], v[112:113], s[72:73], v[86:87] op_sel_hi:[1,0,1]
	v_pk_add_f32 v[118:119], v[122:123], v[118:119]
	v_mov_b32_e32 v122, v94
	v_mov_b32_e32 v123, v102
	v_pk_mov_b32 v[94:95], v[94:95], v[120:121] op_sel:[1,0]
	v_mov_b32_e32 v99, v117
	v_mov_b32_e32 v97, v121
	v_cvt_pk_bf16_f32 v84, v84, v85
	v_cvt_pk_bf16_f32 v85, v86, v87
	v_pk_add_f32 v[94:95], v[122:123], v[94:95]
	v_pk_add_f32 v[96:97], v[98:99], v[96:97]
	global_store_dwordx2 v[108:109], v[84:85], off offset:288
	v_lshlrev_b32_e32 v108, 16, v84
	v_and_b32_e32 v112, 0xffff0000, v84
	v_lshlrev_b32_e32 v84, 16, v85
	v_and_b32_e32 v86, 0xffff0000, v85
	v_pk_add_f32 v[94:95], v[118:119], v[94:95]
	v_pk_add_f32 v[92:93], v[96:97], v[2:3]
	v_mul_f32_e32 v109, v108, v108
	v_mul_f32_e32 v113, v112, v112
	v_mul_f32_e32 v85, v84, v84
	v_mul_f32_e32 v87, v86, v86
	v_pk_add_f32 v[92:93], v[94:95], v[92:93]
	v_pk_add_f32 v[94:95], v[104:105], v[106:107]
	v_pk_add_f32 v[90:91], v[108:109], v[112:113]
	v_pk_add_f32 v[88:89], v[94:95], v[88:89]
	v_pk_add_f32 v[84:85], v[84:85], v[86:87]
	v_pk_add_f32 v[88:89], v[92:93], v[88:89]
	v_pk_add_f32 v[84:85], v[90:91], v[84:85]
	s_nop 0
	v_pk_add_f32 v[84:85], v[88:89], v[84:85]
	ds_bpermute_b32 v86, v181, v84
	ds_bpermute_b32 v87, v181, v85
	s_waitcnt lgkmcnt(0)
	v_pk_add_f32 v[84:85], v[84:85], v[86:87]
	ds_bpermute_b32 v86, v180, v84
	ds_bpermute_b32 v87, v180, v85
	s_and_saveexec_b64 s[0:1], s[40:41]
	v_readlane_b32 s24, v251, 0
	v_readlane_b32 s25, v251, 1
	v_readlane_b32 s26, v251, 2
	v_readlane_b32 s27, v251, 3
	s_mov_b32 s76, 0x30000
	s_cbranch_execz .LBB0_2209
	v_lshl_add_u64 v[88:89], s[50:51], 0, v[100:101]
	v_lshl_add_u64 v[88:89], s[60:61], 2, v[88:89]
	s_waitcnt lgkmcnt(0)
	v_pk_add_f32 v[84:85], v[84:85], v[86:87]
	global_store_dwordx2 v[88:89], v[84:85], off
; __device__ __forceinline__ u32x2 pk4(f32x4 v) { u32x2 r; r.x = pk2(v.x, v.y); r.y = pk2(v.z, v.w); return r; }
;     __device__ __forceinline__ void operator()(int row, int col, f32x4 v, int, float&, float&) const { *(u32x2*)(O + (size_t)row * ldc + col) = pk4(v * s); }
;     __device__ __forceinline__ void operator()(const f32x4 (&acc)[2][2][4][2], const pg8::Unit& u, int wr, int wc, int fr, int fq) const {
; #pragma unroll
;         for (int ai = 0; ai < 2; ++ai)
; #pragma unroll
;             for (int m = 0; m < 4; ++m) {
;                 const int row = u.pm * 256 + ai * 128 + wr * 64 + m * 16 + fr;
;                 float mu = 0.f, rs = 1.f; if (ln) stats_main(stm_p, row, fq, mu, rs);
;                 float s1 = 0.f, s2 = 0.f;
; #pragma unroll
;                 for (int bj = 0; bj < 2; ++bj)
; #pragma unroll
;                     for (int n = 0; n < 2; ++n) {
;                         const int col = u.pn * 256 + bj * 128 + wc * 32 + n * 16 + fq * 4;
;                         const u32x2 raw = *(const u32x2*)(src + (size_t)row * DM + col);
;                         f32x4 x = (f32x4){bflo(raw.x), bfhi(raw.x), bflo(raw.y), bfhi(raw.y)};
;                         if (ln) x = (x - mu) * rs * *(const f32x4*)(g + col) + *(const f32x4*)(b + col);
;                         const u32x2 pz = pk4(x * ALPHA + acc[ai][bj][m][n]);
;                         *(u32x2*)(dst + (size_t)row * DM + col) = pz;
;                         const float z0 = bflo(pz.x), z1 = bfhi(pz.x), z2 = bflo(pz.y), z3 = bfhi(pz.y);
;                         s1 += (z0 + z1) + (z2 + z3); s2 += (z0 * z0 + z1 * z1) + (z2 * z2 + z3 * z3);
;                     }
.LBB0_2209:
	s_or_b64 exec, exec, s[0:1]
	v_or_b32_e32 v94, 48, v146
	v_ashrrev_i32_e32 v95, 31, v94
	v_lshlrev_b64 v[84:85], 7, v[94:95]
	v_lshl_add_u64 v[90:91], v[134:135], 0, v[84:85]
	s_waitcnt lgkmcnt(0)
	s_waitcnt vmcnt(21)
	v_mov_b64_e32 v[86:87], v[206:207]
	v_mov_b64_e32 v[88:89], v[208:209]
	global_load_dwordx4 v[206:209], v[248:249], off offset:-2032
	s_nop 0
	s_waitcnt vmcnt(21)
	v_mov_b64_e32 v[90:91], v[214:215]
	v_mov_b64_e32 v[92:93], v[216:217]
	global_load_dwordx4 v[214:217], v[248:249], off offset:-2048
	s_waitcnt lgkmcnt(0)
	v_pk_add_f32 v[86:87], v[86:87], v[88:89]
	s_waitcnt lgkmcnt(0)
	v_pk_add_f32 v[90:91], v[90:91], v[92:93]
	s_nop 0
	v_pk_add_f32 v[86:87], v[90:91], v[86:87]
	ds_bpermute_b32 v88, v181, v86
	ds_bpermute_b32 v89, v181, v87
	s_waitcnt lgkmcnt(0)
	v_pk_add_f32 v[86:87], v[86:87], v[88:89]
	ds_bpermute_b32 v88, v180, v86
	ds_bpermute_b32 v89, v180, v87
	s_waitcnt lgkmcnt(0)
	v_pk_add_f32 v[86:87], v[86:87], v[88:89]
	s_nop 0
	v_pk_mul_f32 v[96:97], v[86:87], s[82:83] op_sel_hi:[1,0]
	v_lshlrev_b64 v[86:87], 11, v[94:95]
	v_lshl_add_u64 v[86:87], s[70:71], 0, v[86:87]
	v_lshl_add_u64 v[92:93], v[144:145], 1, v[86:87]
	v_add_u32_e32 v243, 0x48000, v242
	s_waitcnt vmcnt(21)
	v_mov_b64_e32 v[86:87], v[234:235]
	global_load_dwordx2 v[234:235], v243, s[70:71]
	v_fma_f32 v3, -v96, v96, v97
	v_max_f32_e32 v3, 0, v3
	v_add_f32_e32 v3, 0x3727c5ac, v3
	v_rsq_f32_e32 v98, v3
	s_waitcnt lgkmcnt(0)
	v_lshlrev_b32_e32 v3, 16, v86
	v_and_b32_e32 v86, 0xffff0000, v86
	v_lshlrev_b32_e32 v88, 16, v87
	v_and_b32_e32 v89, 0xffff0000, v87
	v_sub_f32_e32 v87, v86, v96
	v_sub_f32_e32 v86, v3, v96
	v_sub_f32_e32 v89, v89, v96
	v_sub_f32_e32 v88, v88, v96
	v_pk_mul_f32 v[90:91], v[88:89], v[98:99] op_sel_hi:[1,0]
	v_pk_mul_f32 v[94:95], v[86:87], v[98:99] op_sel_hi:[1,0]
	ds_read_b128 v[86:89], v244
	ds_read_b128 v[100:103], v244 offset:256
	s_waitcnt lgkmcnt(0)
	v_pk_fma_f32 v[88:89], v[88:89], v[90:91], v[102:103]
	s_nop 0
	v_pk_fma_f32 v[82:83], v[88:89], s[72:73], v[82:83] op_sel_hi:[1,0,1]
	s_waitcnt vmcnt(21)
	v_mov_b64_e32 v[88:89], v[236:237]
	global_load_dwordx2 v[236:237], v243, s[70:71] offset:32
	v_pk_fma_f32 v[86:87], v[86:87], v[94:95], v[100:101]
	s_waitcnt lgkmcnt(0)
	v_lshlrev_b32_e32 v3, 16, v88
	v_pk_fma_f32 v[80:81], v[86:87], s[72:73], v[80:81] op_sel_hi:[1,0,1]
	v_cvt_pk_bf16_f32 v87, v82, v83
	v_cvt_pk_bf16_f32 v86, v80, v81
	v_and_b32_e32 v81, 0xffff0000, v88
	v_lshlrev_b32_e32 v83, 16, v89
	v_and_b32_e32 v90, 0xffff0000, v89
	global_store_dwordx2 v[92:93], v[86:87], off
	v_sub_f32_e32 v89, v81, v96
	v_sub_f32_e32 v88, v3, v96
	v_sub_f32_e32 v91, v90, v96
	v_sub_f32_e32 v90, v83, v96
	v_pk_mul_f32 v[94:95], v[98:99], v[90:91] op_sel_hi:[0,1]
	v_pk_mul_f32 v[104:105], v[98:99], v[88:89] op_sel_hi:[0,1]
	ds_read_b128 v[88:91], v244 offset:64
	ds_read_b128 v[100:103], v244 offset:320
	v_and_b32_e32 v82, 0xffff0000, v86
	v_lshlrev_b32_e32 v80, 16, v87
	s_waitcnt lgkmcnt(0)
	v_pk_fma_f32 v[88:89], v[88:89], v[104:105], v[100:101]
	s_nop 0
	v_pk_fma_f32 v[76:77], v[88:89], s[72:73], v[76:77] op_sel_hi:[1,0,1]
	s_waitcnt vmcnt(21)
	v_mov_b64_e32 v[88:89], v[238:239]
	global_load_dwordx2 v[238:239], v243, s[70:71] offset:256
	v_pk_fma_f32 v[90:91], v[90:91], v[94:95], v[102:103]
	v_cvt_pk_bf16_f32 v94, v76, v77
	v_pk_fma_f32 v[78:79], v[90:91], s[72:73], v[78:79] op_sel_hi:[1,0,1]
	s_waitcnt lgkmcnt(0)
	v_lshlrev_b32_e32 v3, 16, v88
	v_cvt_pk_bf16_f32 v95, v78, v79
	v_lshlrev_b32_e32 v78, 16, v95
	v_and_b32_e32 v79, 0xffff0000, v95
	v_mul_f32_e32 v76, v78, v78
	v_pk_fma_f32 v[76:77], v[78:79], v[78:79], v[76:77] op_sel_hi:[1,1,0]
	v_lshlrev_b32_e32 v81, 16, v89
	v_and_b32_e32 v76, 0xffff0000, v88
	v_and_b32_e32 v83, 0xffff0000, v89
	global_store_dwordx2 v[92:93], v[94:95], off offset:32
	v_sub_f32_e32 v89, v76, v96
	v_sub_f32_e32 v88, v3, v96
	v_sub_f32_e32 v91, v83, v96
	v_sub_f32_e32 v90, v81, v96
	v_pk_mul_f32 v[104:105], v[98:99], v[90:91] op_sel_hi:[0,1]
	v_pk_mul_f32 v[106:107], v[98:99], v[88:89] op_sel_hi:[0,1]
	ds_read_b128 v[88:91], v244 offset:128
	ds_read_b128 v[100:103], v244 offset:384
	v_and_b32_e32 v95, 0xffff0000, v94
	s_waitcnt lgkmcnt(0)
	v_pk_fma_f32 v[88:89], v[88:89], v[106:107], v[100:101]
	s_waitcnt vmcnt(21)
	v_mov_b64_e32 v[100:101], v[240:241]
	global_load_dwordx2 v[240:241], v243, s[70:71] offset:288
	v_pk_fma_f32 v[90:91], v[90:91], v[104:105], v[102:103]
	v_pk_fma_f32 v[72:73], v[88:89], s[72:73], v[72:73] op_sel_hi:[1,0,1]
	v_pk_fma_f32 v[74:75], v[90:91], s[72:73], v[74:75] op_sel_hi:[1,0,1]
	v_cvt_pk_bf16_f32 v72, v72, v73
	v_cvt_pk_bf16_f32 v73, v74, v75
	global_store_dwordx2 v[92:93], v[72:73], off offset:256
	v_lshlrev_b32_e32 v88, 16, v72
	v_and_b32_e32 v90, 0xffff0000, v72
	v_lshlrev_b32_e32 v72, 16, v73
	v_and_b32_e32 v74, 0xffff0000, v73
	v_mul_f32_e32 v89, v88, v88
	v_mul_f32_e32 v91, v90, v90
	v_mul_f32_e32 v73, v72, v72
	v_mul_f32_e32 v75, v74, v74
	v_pk_add_f32 v[72:73], v[72:73], v[74:75]
	s_waitcnt lgkmcnt(0)
	v_lshlrev_b32_e32 v3, 16, v100
	v_and_b32_e32 v76, 0xffff0000, v100
	v_lshlrev_b32_e32 v81, 16, v101
	v_and_b32_e32 v83, 0xffff0000, v101
	v_sub_f32_e32 v101, v76, v96
	v_sub_f32_e32 v100, v3, v96
	v_sub_f32_e32 v97, v83, v96
	v_sub_f32_e32 v96, v81, v96
	v_pk_mul_f32 v[96:97], v[98:99], v[96:97] op_sel_hi:[0,1]
	v_pk_mul_f32 v[98:99], v[98:99], v[100:101] op_sel_hi:[0,1]
	ds_read_b128 v[100:103], v244 offset:192
	ds_read_b128 v[104:107], v244 offset:448
	v_mov_b32_e32 v81, v95
	v_mov_b32_e32 v3, v77
	s_waitcnt lgkmcnt(0)
; __device__ __forceinline__ u32x2 pk4(f32x4 v) { u32x2 r; r.x = pk2(v.x, v.y); r.y = pk2(v.z, v.w); return r; }
;     __device__ __forceinline__ void operator()(int row, int col, f32x4 v, int, float&, float&) const { *(u32x2*)(O + (size_t)row * ldc + col) = pk4(v * s); }
;     __device__ __forceinline__ void operator()(const f32x4 (&acc)[2][2][4][2], const pg8::Unit& u, int wr, int wc, int fr, int fq) const {
; #pragma unroll
;         for (int ai = 0; ai < 2; ++ai)
; #pragma unroll
;             for (int m = 0; m < 4; ++m) {
;                 const int row = u.pm * 256 + ai * 128 + wr * 64 + m * 16 + fr;
;                 float mu = 0.f, rs = 1.f; if (ln) stats_main(stm_p, row, fq, mu, rs);
;                 float s1 = 0.f, s2 = 0.f;
; #pragma unroll
;                 for (int bj = 0; bj < 2; ++bj)
; #pragma unroll
;                     for (int n = 0; n < 2; ++n) {
;                         const int col = u.pn * 256 + bj * 128 + wc * 32 + n * 16 + fq * 4;
;                         const u32x2 raw = *(const u32x2*)(src + (size_t)row * DM + col);
;                         f32x4 x = (f32x4){bflo(raw.x), bfhi(raw.x), bflo(raw.y), bfhi(raw.y)};
;                         if (ln) x = (x - mu) * rs * *(const f32x4*)(g + col) + *(const f32x4*)(b + col);
;                         const u32x2 pz = pk4(x * ALPHA + acc[ai][bj][m][n]);
;                         *(u32x2*)(dst + (size_t)row * DM + col) = pz;
;                         const float z0 = bflo(pz.x), z1 = bfhi(pz.x), z2 = bflo(pz.y), z3 = bfhi(pz.y);
;                         s1 += (z0 + z1) + (z2 + z3); s2 += (z0 * z0 + z1 * z1) + (z2 * z2 + z3 * z3);
;                     }
;                 s1 += __shfl_xor(s1, 16); s2 += __shfl_xor(s2, 16); s1 += __shfl_xor(s1, 32); s2 += __shfl_xor(s2, 32);
;                 if (fq == 0) { float* p = stm_n + (size_t)row * 32 + (u.pn * 4 + wc) * 2; p[0] = s1; p[1] = s2; }
	v_pk_fma_f32 v[98:99], v[100:101], v[98:99], v[104:105]
	s_nop 0
	v_pk_fma_f32 v[68:69], v[98:99], s[72:73], v[68:69] op_sel_hi:[1,0,1]
	v_lshlrev_b32_e32 v99, 16, v94
	v_lshlrev_b32_e32 v98, 16, v86
	v_mov_b32_e32 v83, v99
	v_pk_fma_f32 v[96:97], v[102:103], v[96:97], v[106:107]
	v_pk_mul_f32 v[100:101], v[98:99], v[98:99]
	v_pk_mul_f32 v[102:103], v[82:83], v[82:83]
	v_and_b32_e32 v94, 0xffff0000, v87
	v_pk_mul_f32 v[86:87], v[80:81], v[80:81]
	v_pk_mul_f32 v[104:105], v[94:95], v[94:95]
	v_pk_mov_b32 v[106:107], v[98:99], v[100:101] op_sel:[1,0]
	v_pk_mov_b32 v[102:103], v[94:95], v[102:103] op_sel:[1,0]
	v_pk_add_f32 v[82:83], v[98:99], v[82:83]
	v_pk_add_f32 v[80:81], v[94:95], v[80:81]
	v_pk_fma_f32 v[70:71], v[96:97], s[72:73], v[70:71] op_sel_hi:[1,0,1]
	v_pk_add_f32 v[102:103], v[106:107], v[102:103]
	v_mov_b32_e32 v106, v78
	v_mov_b32_e32 v107, v86
	v_pk_mov_b32 v[78:79], v[78:79], v[104:105] op_sel:[1,0]
	v_mov_b32_e32 v83, v101
	v_mov_b32_e32 v81, v105
	v_cvt_pk_bf16_f32 v68, v68, v69
	v_cvt_pk_bf16_f32 v69, v70, v71
	v_pk_add_f32 v[78:79], v[106:107], v[78:79]
	v_pk_add_f32 v[80:81], v[82:83], v[80:81]
	global_store_dwordx2 v[92:93], v[68:69], off offset:288
	v_lshlrev_b32_e32 v92, 16, v68
	v_and_b32_e32 v96, 0xffff0000, v68
	v_lshlrev_b32_e32 v68, 16, v69
	v_and_b32_e32 v70, 0xffff0000, v69
	v_pk_add_f32 v[78:79], v[102:103], v[78:79]
	v_pk_add_f32 v[76:77], v[80:81], v[2:3]
	v_mul_f32_e32 v93, v92, v92
	v_mul_f32_e32 v97, v96, v96
	v_mul_f32_e32 v69, v68, v68
	v_mul_f32_e32 v71, v70, v70
	v_pk_add_f32 v[76:77], v[78:79], v[76:77]
	v_pk_add_f32 v[78:79], v[88:89], v[90:91]
	v_pk_add_f32 v[74:75], v[92:93], v[96:97]
	v_pk_add_f32 v[72:73], v[78:79], v[72:73]
	v_pk_add_f32 v[68:69], v[68:69], v[70:71]
	v_pk_add_f32 v[72:73], v[76:77], v[72:73]
	v_pk_add_f32 v[68:69], v[74:75], v[68:69]
	s_nop 0
	v_pk_add_f32 v[68:69], v[72:73], v[68:69]
	ds_bpermute_b32 v70, v181, v68
	ds_bpermute_b32 v71, v181, v69
	s_waitcnt lgkmcnt(0)
	v_pk_add_f32 v[68:69], v[68:69], v[70:71]
	ds_bpermute_b32 v70, v180, v68
	ds_bpermute_b32 v71, v180, v69
	s_and_saveexec_b64 s[0:1], s[40:41]
	s_cbranch_execz .LBB0_2211
	v_lshl_add_u64 v[72:73], s[50:51], 0, v[84:85]
	v_lshl_add_u64 v[72:73], s[60:61], 2, v[72:73]
	s_waitcnt lgkmcnt(0)
	v_pk_add_f32 v[68:69], v[68:69], v[70:71]
	global_store_dwordx2 v[72:73], v[68:69], off
.LBB0_2211:
	s_or_b64 exec, exec, s[0:1]
	v_add_u32_e32 v78, 0x80, v146
	v_ashrrev_i32_e32 v79, 31, v78
	v_lshlrev_b64 v[68:69], 7, v[78:79]
	v_lshl_add_u64 v[74:75], v[134:135], 0, v[68:69]
	s_waitcnt lgkmcnt(0)
	s_waitcnt vmcnt(21)
	v_mov_b64_e32 v[70:71], v[190:191]
	v_mov_b64_e32 v[72:73], v[192:193]
	global_load_dwordx4 v[190:193], v[248:249], off offset:16
	s_nop 0
	s_waitcnt vmcnt(21)
	v_mov_b64_e32 v[74:75], v[194:195]
	v_mov_b64_e32 v[76:77], v[196:197]
	global_load_dwordx4 v[194:197], v[248:249], off
	s_waitcnt lgkmcnt(0)
	v_pk_add_f32 v[70:71], v[70:71], v[72:73]
	s_waitcnt lgkmcnt(0)
	v_pk_add_f32 v[74:75], v[74:75], v[76:77]
	s_nop 0
	v_pk_add_f32 v[70:71], v[74:75], v[70:71]
	ds_bpermute_b32 v72, v181, v70
	ds_bpermute_b32 v73, v181, v71
	s_waitcnt lgkmcnt(0)
	v_pk_add_f32 v[70:71], v[70:71], v[72:73]
	ds_bpermute_b32 v72, v180, v70
	ds_bpermute_b32 v73, v180, v71
	s_waitcnt lgkmcnt(0)
	v_pk_add_f32 v[70:71], v[70:71], v[72:73]
	s_nop 0
	v_pk_mul_f32 v[80:81], v[70:71], s[82:83] op_sel_hi:[1,0]
	v_lshlrev_b64 v[70:71], 11, v[78:79]
	v_lshl_add_u64 v[70:71], s[70:71], 0, v[70:71]
	v_lshl_add_u64 v[76:77], v[144:145], 1, v[70:71]
	v_add_u32_e32 v243, 0x50000, v242
	s_waitcnt vmcnt(21)
	v_mov_b64_e32 v[70:71], v[198:199]
	global_load_dwordx2 v[198:199], v243, s[70:71]
	v_fma_f32 v3, -v80, v80, v81
	v_max_f32_e32 v3, 0, v3
	v_add_f32_e32 v3, 0x3727c5ac, v3
	v_rsq_f32_e32 v82, v3
	s_waitcnt lgkmcnt(0)
	v_lshlrev_b32_e32 v3, 16, v70
	v_and_b32_e32 v70, 0xffff0000, v70
	v_lshlrev_b32_e32 v72, 16, v71
	v_and_b32_e32 v73, 0xffff0000, v71
	v_sub_f32_e32 v71, v70, v80
	v_sub_f32_e32 v70, v3, v80
	v_sub_f32_e32 v73, v73, v80
	v_sub_f32_e32 v72, v72, v80
	v_pk_mul_f32 v[74:75], v[72:73], v[82:83] op_sel_hi:[1,0]
	v_pk_mul_f32 v[78:79], v[70:71], v[82:83] op_sel_hi:[1,0]
	ds_read_b128 v[70:73], v244
	ds_read_b128 v[84:87], v244 offset:256
	s_waitcnt lgkmcnt(0)
	v_pk_fma_f32 v[72:73], v[72:73], v[74:75], v[86:87]
	s_nop 0
	v_pk_fma_f32 v[66:67], v[72:73], s[72:73], v[66:67] op_sel_hi:[1,0,1]
	s_waitcnt vmcnt(21)
	v_mov_b64_e32 v[72:73], v[200:201]
	global_load_dwordx2 v[200:201], v243, s[70:71] offset:32
	v_pk_fma_f32 v[70:71], v[70:71], v[78:79], v[84:85]
	s_waitcnt lgkmcnt(0)
	v_lshlrev_b32_e32 v3, 16, v72
	v_pk_fma_f32 v[64:65], v[70:71], s[72:73], v[64:65] op_sel_hi:[1,0,1]
	v_cvt_pk_bf16_f32 v71, v66, v67
	v_cvt_pk_bf16_f32 v70, v64, v65
	v_and_b32_e32 v65, 0xffff0000, v72
	v_lshlrev_b32_e32 v67, 16, v73
	v_and_b32_e32 v74, 0xffff0000, v73
	global_store_dwordx2 v[76:77], v[70:71], off
	v_sub_f32_e32 v73, v65, v80
	v_sub_f32_e32 v72, v3, v80
	v_sub_f32_e32 v75, v74, v80
	v_sub_f32_e32 v74, v67, v80
	v_pk_mul_f32 v[78:79], v[82:83], v[74:75] op_sel_hi:[0,1]
	v_pk_mul_f32 v[88:89], v[82:83], v[72:73] op_sel_hi:[0,1]
	ds_read_b128 v[72:75], v244 offset:64
	ds_read_b128 v[84:87], v244 offset:320
	v_and_b32_e32 v66, 0xffff0000, v70
	v_lshlrev_b32_e32 v64, 16, v71
	s_waitcnt lgkmcnt(0)
	v_pk_fma_f32 v[72:73], v[72:73], v[88:89], v[84:85]
	s_nop 0
	v_pk_fma_f32 v[60:61], v[72:73], s[72:73], v[60:61] op_sel_hi:[1,0,1]
	s_waitcnt vmcnt(21)
	v_mov_b64_e32 v[72:73], v[202:203]
	global_load_dwordx2 v[202:203], v243, s[70:71] offset:256
	v_pk_fma_f32 v[74:75], v[74:75], v[78:79], v[86:87]
	v_cvt_pk_bf16_f32 v78, v60, v61
	v_pk_fma_f32 v[62:63], v[74:75], s[72:73], v[62:63] op_sel_hi:[1,0,1]
	s_waitcnt lgkmcnt(0)
; __device__ __forceinline__ u32x2 pk4(f32x4 v) { u32x2 r; r.x = pk2(v.x, v.y); r.y = pk2(v.z, v.w); return r; }
;     __device__ __forceinline__ void operator()(const f32x4 (&acc)[2][2][4][2], const pg8::Unit& u, int wr, int wc, int fr, int fq) const {
;     ...
;                 for (int bj = 0; bj < 2; ++bj)
; #pragma unroll
;                     for (int n = 0; n < 2; ++n) {
;                         const int col = u.pn * 256 + bj * 128 + wc * 32 + n * 16 + fq * 4;
;                         const u32x2 raw = *(const u32x2*)(src + (size_t)row * DM + col);
;                         f32x4 x = (f32x4){bflo(raw.x), bfhi(raw.x), bflo(raw.y), bfhi(raw.y)};
;                         if (ln) x = (x - mu) * rs * *(const f32x4*)(g + col) + *(const f32x4*)(b + col);
;                         const u32x2 pz = pk4(x * ALPHA + acc[ai][bj][m][n]);
;                         *(u32x2*)(dst + (size_t)row * DM + col) = pz;
;                         const float z0 = bflo(pz.x), z1 = bfhi(pz.x), z2 = bflo(pz.y), z3 = bfhi(pz.y);
;                         s1 += (z0 + z1) + (z2 + z3); s2 += (z0 * z0 + z1 * z1) + (z2 * z2 + z3 * z3);
;                     }
;                 s1 += __shfl_xor(s1, 16); s2 += __shfl_xor(s2, 16); s1 += __shfl_xor(s1, 32); s2 += __shfl_xor(s2, 32);
;                 if (fq == 0) { float* p = stm_n + (size_t)row * 32 + (u.pn * 4 + wc) * 2; p[0] = s1; p[1] = s2; }
	v_lshlrev_b32_e32 v3, 16, v72
	v_cvt_pk_bf16_f32 v79, v62, v63
	v_lshlrev_b32_e32 v62, 16, v79
	v_and_b32_e32 v63, 0xffff0000, v79
	v_mul_f32_e32 v60, v62, v62
	v_pk_fma_f32 v[60:61], v[62:63], v[62:63], v[60:61] op_sel_hi:[1,1,0]
	v_lshlrev_b32_e32 v65, 16, v73
	v_and_b32_e32 v60, 0xffff0000, v72
	v_and_b32_e32 v67, 0xffff0000, v73
	global_store_dwordx2 v[76:77], v[78:79], off offset:32
	v_sub_f32_e32 v73, v60, v80
	v_sub_f32_e32 v72, v3, v80
	v_sub_f32_e32 v75, v67, v80
	v_sub_f32_e32 v74, v65, v80
	v_pk_mul_f32 v[88:89], v[82:83], v[74:75] op_sel_hi:[0,1]
	v_pk_mul_f32 v[90:91], v[82:83], v[72:73] op_sel_hi:[0,1]
	ds_read_b128 v[72:75], v244 offset:128
	ds_read_b128 v[84:87], v244 offset:384
	v_and_b32_e32 v79, 0xffff0000, v78
	s_waitcnt lgkmcnt(0)
	v_pk_fma_f32 v[72:73], v[72:73], v[90:91], v[84:85]
	s_waitcnt vmcnt(21)
	v_mov_b64_e32 v[84:85], v[204:205]
	global_load_dwordx2 v[204:205], v243, s[70:71] offset:288
	v_pk_fma_f32 v[74:75], v[74:75], v[88:89], v[86:87]
	v_pk_fma_f32 v[56:57], v[72:73], s[72:73], v[56:57] op_sel_hi:[1,0,1]
	v_pk_fma_f32 v[58:59], v[74:75], s[72:73], v[58:59] op_sel_hi:[1,0,1]
	v_cvt_pk_bf16_f32 v56, v56, v57
	v_cvt_pk_bf16_f32 v57, v58, v59
	global_store_dwordx2 v[76:77], v[56:57], off offset:256
	v_lshlrev_b32_e32 v72, 16, v56
	v_and_b32_e32 v74, 0xffff0000, v56
	v_lshlrev_b32_e32 v56, 16, v57
	v_and_b32_e32 v58, 0xffff0000, v57
	v_mul_f32_e32 v73, v72, v72
	v_mul_f32_e32 v75, v74, v74
	v_mul_f32_e32 v57, v56, v56
	v_mul_f32_e32 v59, v58, v58
	v_pk_add_f32 v[56:57], v[56:57], v[58:59]
	s_waitcnt lgkmcnt(0)
	v_lshlrev_b32_e32 v3, 16, v84
	v_and_b32_e32 v60, 0xffff0000, v84
	v_lshlrev_b32_e32 v65, 16, v85
	v_and_b32_e32 v67, 0xffff0000, v85
	v_sub_f32_e32 v85, v60, v80
	v_sub_f32_e32 v84, v3, v80
	v_sub_f32_e32 v81, v67, v80
	v_sub_f32_e32 v80, v65, v80
	v_pk_mul_f32 v[80:81], v[82:83], v[80:81] op_sel_hi:[0,1]
	v_pk_mul_f32 v[82:83], v[82:83], v[84:85] op_sel_hi:[0,1]
	ds_read_b128 v[84:87], v244 offset:192
	ds_read_b128 v[88:91], v244 offset:448
	v_mov_b32_e32 v65, v79
	v_mov_b32_e32 v3, v61
	s_waitcnt lgkmcnt(0)
	v_pk_fma_f32 v[82:83], v[84:85], v[82:83], v[88:89]
	s_nop 0
	v_pk_fma_f32 v[52:53], v[82:83], s[72:73], v[52:53] op_sel_hi:[1,0,1]
	v_lshlrev_b32_e32 v83, 16, v78
	v_lshlrev_b32_e32 v82, 16, v70
	v_mov_b32_e32 v67, v83
	v_pk_fma_f32 v[80:81], v[86:87], v[80:81], v[90:91]
	v_pk_mul_f32 v[84:85], v[82:83], v[82:83]
	v_pk_mul_f32 v[86:87], v[66:67], v[66:67]
	v_and_b32_e32 v78, 0xffff0000, v71
	v_pk_mul_f32 v[70:71], v[64:65], v[64:65]
	v_pk_mul_f32 v[88:89], v[78:79], v[78:79]
	v_pk_mov_b32 v[90:91], v[82:83], v[84:85] op_sel:[1,0]
	v_pk_mov_b32 v[86:87], v[78:79], v[86:87] op_sel:[1,0]
	v_pk_add_f32 v[66:67], v[82:83], v[66:67]
	v_pk_add_f32 v[64:65], v[78:79], v[64:65]
	v_pk_fma_f32 v[54:55], v[80:81], s[72:73], v[54:55] op_sel_hi:[1,0,1]
	v_pk_add_f32 v[86:87], v[90:91], v[86:87]
	v_mov_b32_e32 v90, v62
	v_mov_b32_e32 v91, v70
	v_pk_mov_b32 v[62:63], v[62:63], v[88:89] op_sel:[1,0]
	v_mov_b32_e32 v67, v85
	v_mov_b32_e32 v65, v89
	v_cvt_pk_bf16_f32 v52, v52, v53
	v_cvt_pk_bf16_f32 v53, v54, v55
	v_pk_add_f32 v[62:63], v[90:91], v[62:63]
	v_pk_add_f32 v[64:65], v[66:67], v[64:65]
	global_store_dwordx2 v[76:77], v[52:53], off offset:288
	v_lshlrev_b32_e32 v76, 16, v52
	v_and_b32_e32 v80, 0xffff0000, v52
	v_lshlrev_b32_e32 v52, 16, v53
	v_and_b32_e32 v54, 0xffff0000, v53
	v_pk_add_f32 v[62:63], v[86:87], v[62:63]
	v_pk_add_f32 v[60:61], v[64:65], v[2:3]
	v_mul_f32_e32 v77, v76, v76
	v_mul_f32_e32 v81, v80, v80
	v_mul_f32_e32 v53, v52, v52
	v_mul_f32_e32 v55, v54, v54
	v_pk_add_f32 v[60:61], v[62:63], v[60:61]
	v_pk_add_f32 v[62:63], v[72:73], v[74:75]
	v_pk_add_f32 v[58:59], v[76:77], v[80:81]
	v_pk_add_f32 v[56:57], v[62:63], v[56:57]
	v_pk_add_f32 v[52:53], v[52:53], v[54:55]
	v_pk_add_f32 v[56:57], v[60:61], v[56:57]
	v_pk_add_f32 v[52:53], v[58:59], v[52:53]
	s_nop 0
	v_pk_add_f32 v[52:53], v[56:57], v[52:53]
	ds_bpermute_b32 v54, v181, v52
	ds_bpermute_b32 v55, v181, v53
	s_waitcnt lgkmcnt(0)
	v_pk_add_f32 v[52:53], v[52:53], v[54:55]
	ds_bpermute_b32 v54, v180, v52
	ds_bpermute_b32 v55, v180, v53
	s_and_saveexec_b64 s[0:1], s[40:41]
	s_cbranch_execz .LBB0_2213
	v_lshl_add_u64 v[56:57], s[50:51], 0, v[68:69]
	v_lshl_add_u64 v[56:57], s[60:61], 2, v[56:57]
	s_waitcnt lgkmcnt(0)
	v_pk_add_f32 v[52:53], v[52:53], v[54:55]
	global_store_dwordx2 v[56:57], v[52:53], off
; __device__ __forceinline__ u32x2 pk4(f32x4 v) { u32x2 r; r.x = pk2(v.x, v.y); r.y = pk2(v.z, v.w); return r; }
;     __device__ __forceinline__ void operator()(int row, int col, f32x4 v, int, float&, float&) const { *(u32x2*)(O + (size_t)row * ldc + col) = pk4(v * s); }
;     __device__ __forceinline__ void operator()(const f32x4 (&acc)[2][2][4][2], const pg8::Unit& u, int wr, int wc, int fr, int fq) const {
; #pragma unroll
;         for (int ai = 0; ai < 2; ++ai)
; #pragma unroll
;             for (int m = 0; m < 4; ++m) {
;                 const int row = u.pm * 256 + ai * 128 + wr * 64 + m * 16 + fr;
;                 float mu = 0.f, rs = 1.f; if (ln) stats_main(stm_p, row, fq, mu, rs);
;                 float s1 = 0.f, s2 = 0.f;
; #pragma unroll
;                 for (int bj = 0; bj < 2; ++bj)
; #pragma unroll
;                     for (int n = 0; n < 2; ++n) {
;                         const int col = u.pn * 256 + bj * 128 + wc * 32 + n * 16 + fq * 4;
;                         const u32x2 raw = *(const u32x2*)(src + (size_t)row * DM + col);
;                         f32x4 x = (f32x4){bflo(raw.x), bfhi(raw.x), bflo(raw.y), bfhi(raw.y)};
;                         if (ln) x = (x - mu) * rs * *(const f32x4*)(g + col) + *(const f32x4*)(b + col);
;                         const u32x2 pz = pk4(x * ALPHA + acc[ai][bj][m][n]);
;                         *(u32x2*)(dst + (size_t)row * DM + col) = pz;
;                         const float z0 = bflo(pz.x), z1 = bfhi(pz.x), z2 = bflo(pz.y), z3 = bfhi(pz.y);
;                         s1 += (z0 + z1) + (z2 + z3); s2 += (z0 * z0 + z1 * z1) + (z2 * z2 + z3 * z3);
;                     }
.LBB0_2213:
	s_or_b64 exec, exec, s[0:1]
	v_add_u32_e32 v62, 0x90, v146
	v_ashrrev_i32_e32 v63, 31, v62
	v_lshlrev_b64 v[52:53], 7, v[62:63]
	v_lshl_add_u64 v[58:59], v[134:135], 0, v[52:53]
	s_waitcnt lgkmcnt(0)
	s_waitcnt vmcnt(21)
	v_mov_b64_e32 v[54:55], v[206:207]
	v_mov_b64_e32 v[56:57], v[208:209]
	global_load_dwordx4 v[206:209], v[248:249], off offset:2064
	s_nop 0
	s_waitcnt vmcnt(21)
	v_mov_b64_e32 v[58:59], v[214:215]
	v_mov_b64_e32 v[60:61], v[216:217]
	global_load_dwordx4 v[214:217], v[248:249], off offset:2048
	s_waitcnt lgkmcnt(0)
	v_pk_add_f32 v[54:55], v[54:55], v[56:57]
	s_waitcnt lgkmcnt(0)
	v_pk_add_f32 v[58:59], v[58:59], v[60:61]
	s_nop 0
	v_pk_add_f32 v[54:55], v[58:59], v[54:55]
	ds_bpermute_b32 v56, v181, v54
	ds_bpermute_b32 v57, v181, v55
	s_waitcnt lgkmcnt(0)
	v_pk_add_f32 v[54:55], v[54:55], v[56:57]
	ds_bpermute_b32 v56, v180, v54
	ds_bpermute_b32 v57, v180, v55
	s_waitcnt lgkmcnt(0)
	v_pk_add_f32 v[54:55], v[54:55], v[56:57]
	s_nop 0
	v_pk_mul_f32 v[64:65], v[54:55], s[82:83] op_sel_hi:[1,0]
	v_lshlrev_b64 v[54:55], 11, v[62:63]
	v_lshl_add_u64 v[54:55], s[70:71], 0, v[54:55]
	v_lshl_add_u64 v[60:61], v[144:145], 1, v[54:55]
	v_add_u32_e32 v243, 0x58000, v242
	s_waitcnt vmcnt(21)
	v_mov_b64_e32 v[54:55], v[234:235]
	global_load_dwordx2 v[234:235], v243, s[70:71]
	v_fma_f32 v3, -v64, v64, v65
	v_max_f32_e32 v3, 0, v3
	v_add_f32_e32 v3, 0x3727c5ac, v3
	v_rsq_f32_e32 v66, v3
	s_waitcnt lgkmcnt(0)
	v_lshlrev_b32_e32 v3, 16, v54
	v_and_b32_e32 v54, 0xffff0000, v54
	v_lshlrev_b32_e32 v56, 16, v55
	v_and_b32_e32 v57, 0xffff0000, v55
	v_sub_f32_e32 v55, v54, v64
	v_sub_f32_e32 v54, v3, v64
	v_sub_f32_e32 v57, v57, v64
	v_sub_f32_e32 v56, v56, v64
	v_pk_mul_f32 v[58:59], v[56:57], v[66:67] op_sel_hi:[1,0]
	v_pk_mul_f32 v[62:63], v[54:55], v[66:67] op_sel_hi:[1,0]
	ds_read_b128 v[54:57], v244
	ds_read_b128 v[68:71], v244 offset:256
	s_waitcnt lgkmcnt(0)
	v_pk_fma_f32 v[56:57], v[56:57], v[58:59], v[70:71]
	s_nop 0
	v_pk_fma_f32 v[50:51], v[56:57], s[72:73], v[50:51] op_sel_hi:[1,0,1]
	s_waitcnt vmcnt(21)
	v_mov_b64_e32 v[56:57], v[236:237]
	global_load_dwordx2 v[236:237], v243, s[70:71] offset:32
	v_pk_fma_f32 v[54:55], v[54:55], v[62:63], v[68:69]
	s_waitcnt lgkmcnt(0)
	v_lshlrev_b32_e32 v3, 16, v56
	v_pk_fma_f32 v[48:49], v[54:55], s[72:73], v[48:49] op_sel_hi:[1,0,1]
	v_cvt_pk_bf16_f32 v55, v50, v51
	v_cvt_pk_bf16_f32 v54, v48, v49
	v_and_b32_e32 v49, 0xffff0000, v56
	v_lshlrev_b32_e32 v51, 16, v57
	v_and_b32_e32 v58, 0xffff0000, v57
	global_store_dwordx2 v[60:61], v[54:55], off
	v_sub_f32_e32 v57, v49, v64
	v_sub_f32_e32 v56, v3, v64
	v_sub_f32_e32 v59, v58, v64
	v_sub_f32_e32 v58, v51, v64
	v_pk_mul_f32 v[62:63], v[66:67], v[58:59] op_sel_hi:[0,1]
	v_pk_mul_f32 v[72:73], v[66:67], v[56:57] op_sel_hi:[0,1]
	ds_read_b128 v[56:59], v244 offset:64
	ds_read_b128 v[68:71], v244 offset:320
	v_and_b32_e32 v50, 0xffff0000, v54
	v_lshlrev_b32_e32 v48, 16, v55
	s_waitcnt lgkmcnt(0)
	v_pk_fma_f32 v[56:57], v[56:57], v[72:73], v[68:69]
	s_nop 0
	v_pk_fma_f32 v[44:45], v[56:57], s[72:73], v[44:45] op_sel_hi:[1,0,1]
	s_waitcnt vmcnt(21)
	v_mov_b64_e32 v[56:57], v[238:239]
	global_load_dwordx2 v[238:239], v243, s[70:71] offset:256
	v_pk_fma_f32 v[58:59], v[58:59], v[62:63], v[70:71]
	v_cvt_pk_bf16_f32 v62, v44, v45
	v_pk_fma_f32 v[46:47], v[58:59], s[72:73], v[46:47] op_sel_hi:[1,0,1]
	s_waitcnt lgkmcnt(0)
	v_lshlrev_b32_e32 v3, 16, v56
	v_cvt_pk_bf16_f32 v63, v46, v47
	v_lshlrev_b32_e32 v46, 16, v63
	v_and_b32_e32 v47, 0xffff0000, v63
	v_mul_f32_e32 v44, v46, v46
	v_pk_fma_f32 v[44:45], v[46:47], v[46:47], v[44:45] op_sel_hi:[1,1,0]
	v_lshlrev_b32_e32 v49, 16, v57
	v_and_b32_e32 v44, 0xffff0000, v56
	v_and_b32_e32 v51, 0xffff0000, v57
	global_store_dwordx2 v[60:61], v[62:63], off offset:32
	v_sub_f32_e32 v57, v44, v64
	v_sub_f32_e32 v56, v3, v64
	v_sub_f32_e32 v59, v51, v64
	v_sub_f32_e32 v58, v49, v64
	v_pk_mul_f32 v[72:73], v[66:67], v[58:59] op_sel_hi:[0,1]
	v_pk_mul_f32 v[74:75], v[66:67], v[56:57] op_sel_hi:[0,1]
	ds_read_b128 v[56:59], v244 offset:128
	ds_read_b128 v[68:71], v244 offset:384
	v_and_b32_e32 v63, 0xffff0000, v62
	s_waitcnt lgkmcnt(0)
	v_pk_fma_f32 v[56:57], v[56:57], v[74:75], v[68:69]
	s_waitcnt vmcnt(21)
	v_mov_b64_e32 v[68:69], v[240:241]
	global_load_dwordx2 v[240:241], v243, s[70:71] offset:288
	v_pk_fma_f32 v[58:59], v[58:59], v[72:73], v[70:71]
	v_pk_fma_f32 v[40:41], v[56:57], s[72:73], v[40:41] op_sel_hi:[1,0,1]
	v_pk_fma_f32 v[42:43], v[58:59], s[72:73], v[42:43] op_sel_hi:[1,0,1]
	v_cvt_pk_bf16_f32 v40, v40, v41
	v_cvt_pk_bf16_f32 v41, v42, v43
	global_store_dwordx2 v[60:61], v[40:41], off offset:256
	v_lshlrev_b32_e32 v56, 16, v40
	v_and_b32_e32 v58, 0xffff0000, v40
	v_lshlrev_b32_e32 v40, 16, v41
	v_and_b32_e32 v42, 0xffff0000, v41
	v_mul_f32_e32 v57, v56, v56
	v_mul_f32_e32 v59, v58, v58
	v_mul_f32_e32 v41, v40, v40
	v_mul_f32_e32 v43, v42, v42
	v_pk_add_f32 v[40:41], v[40:41], v[42:43]
	s_waitcnt lgkmcnt(0)
	v_lshlrev_b32_e32 v3, 16, v68
	v_and_b32_e32 v44, 0xffff0000, v68
	v_lshlrev_b32_e32 v49, 16, v69
	v_and_b32_e32 v51, 0xffff0000, v69
	v_sub_f32_e32 v69, v44, v64
	v_sub_f32_e32 v68, v3, v64
	v_sub_f32_e32 v65, v51, v64
	v_sub_f32_e32 v64, v49, v64
	v_pk_mul_f32 v[64:65], v[66:67], v[64:65] op_sel_hi:[0,1]
	v_pk_mul_f32 v[66:67], v[66:67], v[68:69] op_sel_hi:[0,1]
	ds_read_b128 v[68:71], v244 offset:192
	ds_read_b128 v[72:75], v244 offset:448
	v_mov_b32_e32 v49, v63
	v_mov_b32_e32 v3, v45
	s_waitcnt lgkmcnt(0)
; __device__ __forceinline__ u32x2 pk4(f32x4 v) { u32x2 r; r.x = pk2(v.x, v.y); r.y = pk2(v.z, v.w); return r; }
; __device__ __forceinline__ void stats_main(const float* stm, int row, int fq, float& mu, float& rs) {
;     const f32x4* p = (const f32x4*)(stm + (size_t)row * 32 + fq * 8);
;     const f32x4 a = p[0], b = p[1];
;     float s1 = (a.x + a.z) + (b.x + b.z), s2 = (a.y + a.w) + (b.y + b.w);
;     s1 += __shfl_xor(s1, 16); s2 += __shfl_xor(s2, 16); s1 += __shfl_xor(s1, 32); s2 += __shfl_xor(s2, 32);
;     mu = s1 * (1.f / DM); rs = __builtin_amdgcn_rsqf(fmaxf(s2 * (1.f / DM) - mu * mu, 0.f) + LN_EPS);
; }
;     __device__ __forceinline__ void operator()(const f32x4 (&acc)[2][2][4][2], const pg8::Unit& u, int wr, int wc, int fr, int fq) const {
;     ...
;                 for (int bj = 0; bj < 2; ++bj)
; #pragma unroll
;                     for (int n = 0; n < 2; ++n) {
;                         const int col = u.pn * 256 + bj * 128 + wc * 32 + n * 16 + fq * 4;
;                         const u32x2 raw = *(const u32x2*)(src + (size_t)row * DM + col);
;                         f32x4 x = (f32x4){bflo(raw.x), bfhi(raw.x), bflo(raw.y), bfhi(raw.y)};
;                         if (ln) x = (x - mu) * rs * *(const f32x4*)(g + col) + *(const f32x4*)(b + col);
;                         const u32x2 pz = pk4(x * ALPHA + acc[ai][bj][m][n]);
;                         *(u32x2*)(dst + (size_t)row * DM + col) = pz;
;                         const float z0 = bflo(pz.x), z1 = bfhi(pz.x), z2 = bflo(pz.y), z3 = bfhi(pz.y);
;                         s1 += (z0 + z1) + (z2 + z3); s2 += (z0 * z0 + z1 * z1) + (z2 * z2 + z3 * z3);
;                     }
;                 s1 += __shfl_xor(s1, 16); s2 += __shfl_xor(s2, 16); s1 += __shfl_xor(s1, 32); s2 += __shfl_xor(s2, 32);
;                 if (fq == 0) { float* p = stm_n + (size_t)row * 32 + (u.pn * 4 + wc) * 2; p[0] = s1; p[1] = s2; }
	v_pk_fma_f32 v[66:67], v[68:69], v[66:67], v[72:73]
	s_nop 0
	v_pk_fma_f32 v[36:37], v[66:67], s[72:73], v[36:37] op_sel_hi:[1,0,1]
	v_lshlrev_b32_e32 v67, 16, v62
	v_lshlrev_b32_e32 v66, 16, v54
	v_mov_b32_e32 v51, v67
	v_pk_fma_f32 v[64:65], v[70:71], v[64:65], v[74:75]
	v_pk_mul_f32 v[68:69], v[66:67], v[66:67]
	v_pk_mul_f32 v[70:71], v[50:51], v[50:51]
	v_and_b32_e32 v62, 0xffff0000, v55
	v_pk_mul_f32 v[54:55], v[48:49], v[48:49]
	v_pk_mul_f32 v[72:73], v[62:63], v[62:63]
	v_pk_mov_b32 v[74:75], v[66:67], v[68:69] op_sel:[1,0]
	v_pk_mov_b32 v[70:71], v[62:63], v[70:71] op_sel:[1,0]
	v_pk_add_f32 v[50:51], v[66:67], v[50:51]
	v_pk_add_f32 v[48:49], v[62:63], v[48:49]
	v_pk_fma_f32 v[38:39], v[64:65], s[72:73], v[38:39] op_sel_hi:[1,0,1]
	v_pk_add_f32 v[70:71], v[74:75], v[70:71]
	v_mov_b32_e32 v74, v46
	v_mov_b32_e32 v75, v54
	v_pk_mov_b32 v[46:47], v[46:47], v[72:73] op_sel:[1,0]
	v_mov_b32_e32 v51, v69
	v_mov_b32_e32 v49, v73
	v_cvt_pk_bf16_f32 v36, v36, v37
	v_cvt_pk_bf16_f32 v37, v38, v39
	v_pk_add_f32 v[46:47], v[74:75], v[46:47]
	v_pk_add_f32 v[48:49], v[50:51], v[48:49]
	global_store_dwordx2 v[60:61], v[36:37], off offset:288
	v_lshlrev_b32_e32 v60, 16, v36
	v_and_b32_e32 v64, 0xffff0000, v36
	v_lshlrev_b32_e32 v36, 16, v37
	v_and_b32_e32 v38, 0xffff0000, v37
	v_pk_add_f32 v[46:47], v[70:71], v[46:47]
	v_pk_add_f32 v[44:45], v[48:49], v[2:3]
	v_mul_f32_e32 v61, v60, v60
	v_mul_f32_e32 v65, v64, v64
	v_mul_f32_e32 v37, v36, v36
	v_mul_f32_e32 v39, v38, v38
	v_pk_add_f32 v[44:45], v[46:47], v[44:45]
	v_pk_add_f32 v[46:47], v[56:57], v[58:59]
	v_pk_add_f32 v[42:43], v[60:61], v[64:65]
	v_pk_add_f32 v[40:41], v[46:47], v[40:41]
	v_pk_add_f32 v[36:37], v[36:37], v[38:39]
	v_pk_add_f32 v[40:41], v[44:45], v[40:41]
	v_pk_add_f32 v[36:37], v[42:43], v[36:37]
	s_nop 0
	v_pk_add_f32 v[36:37], v[40:41], v[36:37]
	ds_bpermute_b32 v38, v181, v36
	ds_bpermute_b32 v39, v181, v37
	s_waitcnt lgkmcnt(0)
	v_pk_add_f32 v[36:37], v[36:37], v[38:39]
	ds_bpermute_b32 v38, v180, v36
	ds_bpermute_b32 v39, v180, v37
	s_and_saveexec_b64 s[0:1], s[40:41]
	s_cbranch_execz .LBB0_2215
	v_lshl_add_u64 v[40:41], s[50:51], 0, v[52:53]
	v_lshl_add_u64 v[40:41], s[60:61], 2, v[40:41]
	s_waitcnt lgkmcnt(0)
	v_pk_add_f32 v[36:37], v[36:37], v[38:39]
	global_store_dwordx2 v[40:41], v[36:37], off
.LBB0_2215:
	s_or_b64 exec, exec, s[0:1]
	v_add_u32_e32 v46, 0xa0, v146
	v_ashrrev_i32_e32 v47, 31, v46
	v_lshlrev_b64 v[36:37], 7, v[46:47]
	v_lshl_add_u64 v[42:43], v[134:135], 0, v[36:37]
	s_waitcnt lgkmcnt(0)
	s_waitcnt vmcnt(21)
	v_mov_b64_e32 v[38:39], v[190:191]
	v_mov_b64_e32 v[40:41], v[192:193]
	s_nop 0
	s_waitcnt vmcnt(20)
	v_mov_b64_e32 v[42:43], v[194:195]
	v_mov_b64_e32 v[44:45], v[196:197]
	s_waitcnt lgkmcnt(0)
	v_pk_add_f32 v[38:39], v[38:39], v[40:41]
	s_waitcnt lgkmcnt(0)
	v_pk_add_f32 v[42:43], v[42:43], v[44:45]
	s_nop 0
	v_pk_add_f32 v[38:39], v[42:43], v[38:39]
	ds_bpermute_b32 v40, v181, v38
	ds_bpermute_b32 v41, v181, v39
	s_waitcnt lgkmcnt(0)
	v_pk_add_f32 v[38:39], v[38:39], v[40:41]
	ds_bpermute_b32 v40, v180, v38
	ds_bpermute_b32 v41, v180, v39
	s_waitcnt lgkmcnt(0)
	v_pk_add_f32 v[38:39], v[38:39], v[40:41]
	s_nop 0
	v_pk_mul_f32 v[48:49], v[38:39], s[82:83] op_sel_hi:[1,0]
	v_lshlrev_b64 v[38:39], 11, v[46:47]
	v_lshl_add_u64 v[38:39], s[70:71], 0, v[38:39]
	v_lshl_add_u64 v[44:45], v[144:145], 1, v[38:39]
	s_waitcnt vmcnt(19)
	v_mov_b64_e32 v[38:39], v[198:199]
	v_fma_f32 v3, -v48, v48, v49
	v_max_f32_e32 v3, 0, v3
	v_add_f32_e32 v3, 0x3727c5ac, v3
	v_rsq_f32_e32 v50, v3
	s_waitcnt lgkmcnt(0)
	v_lshlrev_b32_e32 v3, 16, v38
	v_and_b32_e32 v38, 0xffff0000, v38
	v_lshlrev_b32_e32 v40, 16, v39
	v_and_b32_e32 v41, 0xffff0000, v39
	v_sub_f32_e32 v39, v38, v48
	v_sub_f32_e32 v38, v3, v48
	v_sub_f32_e32 v41, v41, v48
	v_sub_f32_e32 v40, v40, v48
	v_pk_mul_f32 v[42:43], v[40:41], v[50:51] op_sel_hi:[1,0]
	v_pk_mul_f32 v[46:47], v[38:39], v[50:51] op_sel_hi:[1,0]
	ds_read_b128 v[38:41], v244
	ds_read_b128 v[52:55], v244 offset:256
	s_waitcnt lgkmcnt(0)
	v_pk_fma_f32 v[40:41], v[40:41], v[42:43], v[54:55]
	s_nop 0
	v_pk_fma_f32 v[34:35], v[40:41], s[72:73], v[34:35] op_sel_hi:[1,0,1]
	s_waitcnt vmcnt(18)
	v_mov_b64_e32 v[40:41], v[200:201]
	v_pk_fma_f32 v[38:39], v[38:39], v[46:47], v[52:53]
	s_waitcnt lgkmcnt(0)
	v_lshlrev_b32_e32 v3, 16, v40
	v_pk_fma_f32 v[32:33], v[38:39], s[72:73], v[32:33] op_sel_hi:[1,0,1]
	v_cvt_pk_bf16_f32 v39, v34, v35
	v_cvt_pk_bf16_f32 v38, v32, v33
	v_and_b32_e32 v33, 0xffff0000, v40
	v_lshlrev_b32_e32 v35, 16, v41
	v_and_b32_e32 v42, 0xffff0000, v41
	global_store_dwordx2 v[44:45], v[38:39], off
	v_sub_f32_e32 v41, v33, v48
	v_sub_f32_e32 v40, v3, v48
	v_sub_f32_e32 v43, v42, v48
	v_sub_f32_e32 v42, v35, v48
	v_pk_mul_f32 v[46:47], v[50:51], v[42:43] op_sel_hi:[0,1]
	v_pk_mul_f32 v[56:57], v[50:51], v[40:41] op_sel_hi:[0,1]
	ds_read_b128 v[40:43], v244 offset:64
	ds_read_b128 v[52:55], v244 offset:320
	v_and_b32_e32 v34, 0xffff0000, v38
	v_lshlrev_b32_e32 v32, 16, v39
	s_waitcnt lgkmcnt(0)
	v_pk_fma_f32 v[40:41], v[40:41], v[56:57], v[52:53]
	s_nop 0
	v_pk_fma_f32 v[28:29], v[40:41], s[72:73], v[28:29] op_sel_hi:[1,0,1]
	s_waitcnt vmcnt(17)
	v_mov_b64_e32 v[40:41], v[202:203]
	v_pk_fma_f32 v[42:43], v[42:43], v[46:47], v[54:55]
	v_cvt_pk_bf16_f32 v46, v28, v29
	v_pk_fma_f32 v[30:31], v[42:43], s[72:73], v[30:31] op_sel_hi:[1,0,1]
	s_waitcnt lgkmcnt(0)
; __device__ __forceinline__ u32x2 pk4(f32x4 v) { u32x2 r; r.x = pk2(v.x, v.y); r.y = pk2(v.z, v.w); return r; }
;     __device__ __forceinline__ void operator()(const f32x4 (&acc)[2][2][4][2], const pg8::Unit& u, int wr, int wc, int fr, int fq) const {
;     ...
;                 for (int bj = 0; bj < 2; ++bj)
; #pragma unroll
;                     for (int n = 0; n < 2; ++n) {
;                         const int col = u.pn * 256 + bj * 128 + wc * 32 + n * 16 + fq * 4;
;                         const u32x2 raw = *(const u32x2*)(src + (size_t)row * DM + col);
;                         f32x4 x = (f32x4){bflo(raw.x), bfhi(raw.x), bflo(raw.y), bfhi(raw.y)};
;                         if (ln) x = (x - mu) * rs * *(const f32x4*)(g + col) + *(const f32x4*)(b + col);
;                         const u32x2 pz = pk4(x * ALPHA + acc[ai][bj][m][n]);
;                         *(u32x2*)(dst + (size_t)row * DM + col) = pz;
;                         const float z0 = bflo(pz.x), z1 = bfhi(pz.x), z2 = bflo(pz.y), z3 = bfhi(pz.y);
;                         s1 += (z0 + z1) + (z2 + z3); s2 += (z0 * z0 + z1 * z1) + (z2 * z2 + z3 * z3);
;                     }
;                 s1 += __shfl_xor(s1, 16); s2 += __shfl_xor(s2, 16); s1 += __shfl_xor(s1, 32); s2 += __shfl_xor(s2, 32);
;                 if (fq == 0) { float* p = stm_n + (size_t)row * 32 + (u.pn * 4 + wc) * 2; p[0] = s1; p[1] = s2; }
	v_lshlrev_b32_e32 v3, 16, v40
	v_cvt_pk_bf16_f32 v47, v30, v31
	v_lshlrev_b32_e32 v30, 16, v47
	v_and_b32_e32 v31, 0xffff0000, v47
	v_mul_f32_e32 v28, v30, v30
	v_pk_fma_f32 v[28:29], v[30:31], v[30:31], v[28:29] op_sel_hi:[1,1,0]
	v_lshlrev_b32_e32 v33, 16, v41
	v_and_b32_e32 v28, 0xffff0000, v40
	v_and_b32_e32 v35, 0xffff0000, v41
	global_store_dwordx2 v[44:45], v[46:47], off offset:32
	v_sub_f32_e32 v41, v28, v48
	v_sub_f32_e32 v40, v3, v48
	v_sub_f32_e32 v43, v35, v48
	v_sub_f32_e32 v42, v33, v48
	v_pk_mul_f32 v[56:57], v[50:51], v[42:43] op_sel_hi:[0,1]
	v_pk_mul_f32 v[58:59], v[50:51], v[40:41] op_sel_hi:[0,1]
	ds_read_b128 v[40:43], v244 offset:128
	ds_read_b128 v[52:55], v244 offset:384
	v_and_b32_e32 v47, 0xffff0000, v46
	s_waitcnt lgkmcnt(0)
	v_pk_fma_f32 v[40:41], v[40:41], v[58:59], v[52:53]
	s_waitcnt vmcnt(16)
	v_mov_b64_e32 v[52:53], v[204:205]
	v_pk_fma_f32 v[42:43], v[42:43], v[56:57], v[54:55]
	v_pk_fma_f32 v[24:25], v[40:41], s[72:73], v[24:25] op_sel_hi:[1,0,1]
	v_pk_fma_f32 v[26:27], v[42:43], s[72:73], v[26:27] op_sel_hi:[1,0,1]
	v_cvt_pk_bf16_f32 v24, v24, v25
	v_cvt_pk_bf16_f32 v25, v26, v27
	global_store_dwordx2 v[44:45], v[24:25], off offset:256
	v_lshlrev_b32_e32 v40, 16, v24
	v_and_b32_e32 v42, 0xffff0000, v24
	v_lshlrev_b32_e32 v24, 16, v25
	v_and_b32_e32 v26, 0xffff0000, v25
	v_mul_f32_e32 v41, v40, v40
	v_mul_f32_e32 v43, v42, v42
	v_mul_f32_e32 v25, v24, v24
	v_mul_f32_e32 v27, v26, v26
	v_pk_add_f32 v[24:25], v[24:25], v[26:27]
	s_waitcnt lgkmcnt(0)
	v_lshlrev_b32_e32 v3, 16, v52
	v_and_b32_e32 v28, 0xffff0000, v52
	v_lshlrev_b32_e32 v33, 16, v53
	v_and_b32_e32 v35, 0xffff0000, v53
	v_sub_f32_e32 v53, v28, v48
	v_sub_f32_e32 v52, v3, v48
	v_sub_f32_e32 v49, v35, v48
	v_sub_f32_e32 v48, v33, v48
	v_pk_mul_f32 v[48:49], v[50:51], v[48:49] op_sel_hi:[0,1]
	v_pk_mul_f32 v[50:51], v[50:51], v[52:53] op_sel_hi:[0,1]
	ds_read_b128 v[52:55], v244 offset:192
	ds_read_b128 v[56:59], v244 offset:448
	v_mov_b32_e32 v33, v47
	v_mov_b32_e32 v3, v29
	s_waitcnt lgkmcnt(0)
	v_pk_fma_f32 v[50:51], v[52:53], v[50:51], v[56:57]
	s_nop 0
	v_pk_fma_f32 v[20:21], v[50:51], s[72:73], v[20:21] op_sel_hi:[1,0,1]
	v_lshlrev_b32_e32 v51, 16, v46
	v_lshlrev_b32_e32 v50, 16, v38
	v_mov_b32_e32 v35, v51
	v_pk_fma_f32 v[48:49], v[54:55], v[48:49], v[58:59]
	v_pk_mul_f32 v[52:53], v[50:51], v[50:51]
	v_pk_mul_f32 v[54:55], v[34:35], v[34:35]
	v_and_b32_e32 v46, 0xffff0000, v39
	v_pk_mul_f32 v[38:39], v[32:33], v[32:33]
	v_pk_mul_f32 v[56:57], v[46:47], v[46:47]
	v_pk_mov_b32 v[58:59], v[50:51], v[52:53] op_sel:[1,0]
	v_pk_mov_b32 v[54:55], v[46:47], v[54:55] op_sel:[1,0]
	v_pk_add_f32 v[34:35], v[50:51], v[34:35]
	v_pk_add_f32 v[32:33], v[46:47], v[32:33]
	v_pk_fma_f32 v[22:23], v[48:49], s[72:73], v[22:23] op_sel_hi:[1,0,1]
	v_pk_add_f32 v[54:55], v[58:59], v[54:55]
	v_mov_b32_e32 v58, v30
	v_mov_b32_e32 v59, v38
	v_pk_mov_b32 v[30:31], v[30:31], v[56:57] op_sel:[1,0]
	v_mov_b32_e32 v35, v53
	v_mov_b32_e32 v33, v57
	v_cvt_pk_bf16_f32 v20, v20, v21
	v_cvt_pk_bf16_f32 v21, v22, v23
	v_pk_add_f32 v[30:31], v[58:59], v[30:31]
	v_pk_add_f32 v[32:33], v[34:35], v[32:33]
	global_store_dwordx2 v[44:45], v[20:21], off offset:288
	v_lshlrev_b32_e32 v44, 16, v20
	v_and_b32_e32 v48, 0xffff0000, v20
	v_lshlrev_b32_e32 v20, 16, v21
	v_and_b32_e32 v22, 0xffff0000, v21
	v_pk_add_f32 v[30:31], v[54:55], v[30:31]
	v_pk_add_f32 v[28:29], v[32:33], v[2:3]
	v_mul_f32_e32 v45, v44, v44
	v_mul_f32_e32 v49, v48, v48
	v_mul_f32_e32 v21, v20, v20
	v_mul_f32_e32 v23, v22, v22
	v_pk_add_f32 v[28:29], v[30:31], v[28:29]
	v_pk_add_f32 v[30:31], v[40:41], v[42:43]
	v_pk_add_f32 v[26:27], v[44:45], v[48:49]
	v_pk_add_f32 v[24:25], v[30:31], v[24:25]
	v_pk_add_f32 v[20:21], v[20:21], v[22:23]
	v_pk_add_f32 v[24:25], v[28:29], v[24:25]
	v_pk_add_f32 v[20:21], v[26:27], v[20:21]
	s_nop 0
	v_pk_add_f32 v[20:21], v[24:25], v[20:21]
	ds_bpermute_b32 v22, v181, v20
	ds_bpermute_b32 v23, v181, v21
	s_waitcnt lgkmcnt(0)
	v_pk_add_f32 v[20:21], v[20:21], v[22:23]
	ds_bpermute_b32 v22, v180, v20
	ds_bpermute_b32 v23, v180, v21
	s_and_saveexec_b64 s[0:1], s[40:41]
	s_cbranch_execz .LBB0_2217
	v_lshl_add_u64 v[24:25], s[50:51], 0, v[36:37]
	v_lshl_add_u64 v[24:25], s[60:61], 2, v[24:25]
	s_waitcnt lgkmcnt(0)
	v_pk_add_f32 v[20:21], v[20:21], v[22:23]
	global_store_dwordx2 v[24:25], v[20:21], off
; __device__ __forceinline__ u32x2 pk4(f32x4 v) { u32x2 r; r.x = pk2(v.x, v.y); r.y = pk2(v.z, v.w); return r; }
;     __device__ __forceinline__ void operator()(int row, int col, f32x4 v, int, float&, float&) const { *(u32x2*)(O + (size_t)row * ldc + col) = pk4(v * s); }
; __device__ __forceinline__ void stats_main(const float* stm, int row, int fq, float& mu, float& rs) {
;     const f32x4* p = (const f32x4*)(stm + (size_t)row * 32 + fq * 8);
;     const f32x4 a = p[0], b = p[1];
;     float s1 = (a.x + a.z) + (b.x + b.z), s2 = (a.y + a.w) + (b.y + b.w);
;     s1 += __shfl_xor(s1, 16); s2 += __shfl_xor(s2, 16); s1 += __shfl_xor(s1, 32); s2 += __shfl_xor(s2, 32);
;     mu = s1 * (1.f / DM); rs = __builtin_amdgcn_rsqf(fmaxf(s2 * (1.f / DM) - mu * mu, 0.f) + LN_EPS);
; }
;     __device__ __forceinline__ void operator()(const f32x4 (&acc)[2][2][4][2], const pg8::Unit& u, int wr, int wc, int fr, int fq) const {
; #pragma unroll
;         for (int ai = 0; ai < 2; ++ai)
; #pragma unroll
;             for (int m = 0; m < 4; ++m) {
;                 const int row = u.pm * 256 + ai * 128 + wr * 64 + m * 16 + fr;
;                 float mu = 0.f, rs = 1.f; if (ln) stats_main(stm_p, row, fq, mu, rs);
;                 float s1 = 0.f, s2 = 0.f;
; #pragma unroll
;                 for (int bj = 0; bj < 2; ++bj)
; #pragma unroll
;                     for (int n = 0; n < 2; ++n) {
;                         const int col = u.pn * 256 + bj * 128 + wc * 32 + n * 16 + fq * 4;
;                         const u32x2 raw = *(const u32x2*)(src + (size_t)row * DM + col);
;                         f32x4 x = (f32x4){bflo(raw.x), bfhi(raw.x), bflo(raw.y), bfhi(raw.y)};
;                         if (ln) x = (x - mu) * rs * *(const f32x4*)(g + col) + *(const f32x4*)(b + col);
;                         const u32x2 pz = pk4(x * ALPHA + acc[ai][bj][m][n]);
;                         *(u32x2*)(dst + (size_t)row * DM + col) = pz;
.LBB0_2217:
	s_or_b64 exec, exec, s[0:1]
	v_add_u32_e32 v30, 0xb0, v146
	v_ashrrev_i32_e32 v31, 31, v30
	v_lshlrev_b64 v[20:21], 7, v[30:31]
	v_lshl_add_u64 v[26:27], v[134:135], 0, v[20:21]
	s_waitcnt lgkmcnt(0)
	s_waitcnt vmcnt(15)
	v_mov_b64_e32 v[22:23], v[206:207]
	v_mov_b64_e32 v[24:25], v[208:209]
	s_nop 0
	s_waitcnt vmcnt(14)
	v_mov_b64_e32 v[26:27], v[214:215]
	v_mov_b64_e32 v[28:29], v[216:217]
	s_waitcnt lgkmcnt(0)
	v_pk_add_f32 v[22:23], v[22:23], v[24:25]
	s_waitcnt lgkmcnt(0)
	v_pk_add_f32 v[26:27], v[26:27], v[28:29]
	s_nop 0
	v_pk_add_f32 v[22:23], v[26:27], v[22:23]
	ds_bpermute_b32 v24, v181, v22
	ds_bpermute_b32 v25, v181, v23
	s_waitcnt lgkmcnt(0)
	v_pk_add_f32 v[22:23], v[22:23], v[24:25]
	ds_bpermute_b32 v24, v180, v22
	ds_bpermute_b32 v25, v180, v23
	s_waitcnt lgkmcnt(0)
	v_pk_add_f32 v[22:23], v[22:23], v[24:25]
	s_nop 0
	v_pk_mul_f32 v[32:33], v[22:23], s[82:83] op_sel_hi:[1,0]
	v_lshlrev_b64 v[22:23], 11, v[30:31]
	v_lshl_add_u64 v[22:23], s[70:71], 0, v[22:23]
	v_lshl_add_u64 v[28:29], v[144:145], 1, v[22:23]
	s_waitcnt vmcnt(13)
	v_mov_b64_e32 v[22:23], v[234:235]
	v_fma_f32 v3, -v32, v32, v33
	v_max_f32_e32 v3, 0, v3
	v_add_f32_e32 v3, 0x3727c5ac, v3
	v_rsq_f32_e32 v34, v3
	s_waitcnt lgkmcnt(0)
	v_lshlrev_b32_e32 v3, 16, v22
	v_and_b32_e32 v22, 0xffff0000, v22
	v_lshlrev_b32_e32 v24, 16, v23
	v_and_b32_e32 v25, 0xffff0000, v23
	v_sub_f32_e32 v23, v22, v32
	v_sub_f32_e32 v22, v3, v32
	v_sub_f32_e32 v25, v25, v32
	v_sub_f32_e32 v24, v24, v32
	v_pk_mul_f32 v[26:27], v[24:25], v[34:35] op_sel_hi:[1,0]
	v_pk_mul_f32 v[30:31], v[22:23], v[34:35] op_sel_hi:[1,0]
	ds_read_b128 v[22:25], v244
	ds_read_b128 v[36:39], v244 offset:256
	s_waitcnt lgkmcnt(0)
	v_pk_fma_f32 v[24:25], v[24:25], v[26:27], v[38:39]
	s_nop 0
	v_pk_fma_f32 v[18:19], v[24:25], s[72:73], v[18:19] op_sel_hi:[1,0,1]
	s_waitcnt vmcnt(12)
	v_mov_b64_e32 v[24:25], v[236:237]
	v_pk_fma_f32 v[22:23], v[22:23], v[30:31], v[36:37]
	s_waitcnt lgkmcnt(0)
	v_lshlrev_b32_e32 v3, 16, v24
	v_pk_fma_f32 v[16:17], v[22:23], s[72:73], v[16:17] op_sel_hi:[1,0,1]
	v_cvt_pk_bf16_f32 v23, v18, v19
	v_cvt_pk_bf16_f32 v22, v16, v17
	v_and_b32_e32 v17, 0xffff0000, v24
	v_lshlrev_b32_e32 v19, 16, v25
	v_and_b32_e32 v26, 0xffff0000, v25
	global_store_dwordx2 v[28:29], v[22:23], off
	v_sub_f32_e32 v25, v17, v32
	v_sub_f32_e32 v24, v3, v32
	v_sub_f32_e32 v27, v26, v32
	v_sub_f32_e32 v26, v19, v32
	v_pk_mul_f32 v[30:31], v[34:35], v[26:27] op_sel_hi:[0,1]
	v_pk_mul_f32 v[40:41], v[34:35], v[24:25] op_sel_hi:[0,1]
	ds_read_b128 v[24:27], v244 offset:64
	ds_read_b128 v[36:39], v244 offset:320
	v_and_b32_e32 v18, 0xffff0000, v22
	v_lshlrev_b32_e32 v16, 16, v23
	s_waitcnt lgkmcnt(0)
	v_pk_fma_f32 v[24:25], v[24:25], v[40:41], v[36:37]
	s_nop 0
	v_pk_fma_f32 v[12:13], v[24:25], s[72:73], v[12:13] op_sel_hi:[1,0,1]
	s_waitcnt vmcnt(11)
	v_mov_b64_e32 v[24:25], v[238:239]
	v_pk_fma_f32 v[26:27], v[26:27], v[30:31], v[38:39]
	v_cvt_pk_bf16_f32 v30, v12, v13
	v_pk_fma_f32 v[14:15], v[26:27], s[72:73], v[14:15] op_sel_hi:[1,0,1]
	s_waitcnt lgkmcnt(0)
	v_lshlrev_b32_e32 v3, 16, v24
	v_cvt_pk_bf16_f32 v31, v14, v15
	v_lshlrev_b32_e32 v14, 16, v31
	v_and_b32_e32 v15, 0xffff0000, v31
	v_mul_f32_e32 v12, v14, v14
	v_pk_fma_f32 v[12:13], v[14:15], v[14:15], v[12:13] op_sel_hi:[1,1,0]
	v_lshlrev_b32_e32 v17, 16, v25
	v_and_b32_e32 v12, 0xffff0000, v24
	v_and_b32_e32 v19, 0xffff0000, v25
	global_store_dwordx2 v[28:29], v[30:31], off offset:32
	v_sub_f32_e32 v25, v12, v32
	v_sub_f32_e32 v24, v3, v32
	v_sub_f32_e32 v27, v19, v32
	v_sub_f32_e32 v26, v17, v32
	v_pk_mul_f32 v[40:41], v[34:35], v[26:27] op_sel_hi:[0,1]
	v_pk_mul_f32 v[42:43], v[34:35], v[24:25] op_sel_hi:[0,1]
	ds_read_b128 v[24:27], v244 offset:128
	ds_read_b128 v[36:39], v244 offset:384
	v_and_b32_e32 v31, 0xffff0000, v30
	s_waitcnt lgkmcnt(0)
; __device__ __forceinline__ u32x2 pk4(f32x4 v) { u32x2 r; r.x = pk2(v.x, v.y); r.y = pk2(v.z, v.w); return r; }
;     __device__ __forceinline__ void operator()(const f32x4 (&acc)[2][2][4][2], const pg8::Unit& u, int wr, int wc, int fr, int fq) const {
;     ...
;                         const u32x2 raw = *(const u32x2*)(src + (size_t)row * DM + col);
;                         f32x4 x = (f32x4){bflo(raw.x), bfhi(raw.x), bflo(raw.y), bfhi(raw.y)};
;                         if (ln) x = (x - mu) * rs * *(const f32x4*)(g + col) + *(const f32x4*)(b + col);
;                         const u32x2 pz = pk4(x * ALPHA + acc[ai][bj][m][n]);
;                         *(u32x2*)(dst + (size_t)row * DM + col) = pz;
;                         const float z0 = bflo(pz.x), z1 = bfhi(pz.x), z2 = bflo(pz.y), z3 = bfhi(pz.y);
;                         s1 += (z0 + z1) + (z2 + z3); s2 += (z0 * z0 + z1 * z1) + (z2 * z2 + z3 * z3);
;                     }
;                 s1 += __shfl_xor(s1, 16); s2 += __shfl_xor(s2, 16); s1 += __shfl_xor(s1, 32); s2 += __shfl_xor(s2, 32);
;                 if (fq == 0) { float* p = stm_n + (size_t)row * 32 + (u.pn * 4 + wc) * 2; p[0] = s1; p[1] = s2; }
	v_pk_fma_f32 v[24:25], v[24:25], v[42:43], v[36:37]
	s_waitcnt vmcnt(10)
	v_mov_b64_e32 v[36:37], v[240:241]
	v_pk_fma_f32 v[26:27], v[26:27], v[40:41], v[38:39]
	v_pk_fma_f32 v[8:9], v[24:25], s[72:73], v[8:9] op_sel_hi:[1,0,1]
	v_pk_fma_f32 v[10:11], v[26:27], s[72:73], v[10:11] op_sel_hi:[1,0,1]
	v_cvt_pk_bf16_f32 v8, v8, v9
	v_cvt_pk_bf16_f32 v9, v10, v11
	global_store_dwordx2 v[28:29], v[8:9], off offset:256
	v_lshlrev_b32_e32 v24, 16, v8
	v_and_b32_e32 v26, 0xffff0000, v8
	v_lshlrev_b32_e32 v8, 16, v9
	v_and_b32_e32 v10, 0xffff0000, v9
	v_mul_f32_e32 v25, v24, v24
	v_mul_f32_e32 v27, v26, v26
	v_mul_f32_e32 v9, v8, v8
	v_mul_f32_e32 v11, v10, v10
	v_pk_add_f32 v[8:9], v[8:9], v[10:11]
	s_waitcnt lgkmcnt(0)
	v_lshlrev_b32_e32 v3, 16, v36
	v_and_b32_e32 v12, 0xffff0000, v36
	v_lshlrev_b32_e32 v17, 16, v37
	v_and_b32_e32 v19, 0xffff0000, v37
	v_sub_f32_e32 v37, v12, v32
	v_sub_f32_e32 v36, v3, v32
	v_sub_f32_e32 v33, v19, v32
	v_sub_f32_e32 v32, v17, v32
	v_pk_mul_f32 v[32:33], v[34:35], v[32:33] op_sel_hi:[0,1]
	v_pk_mul_f32 v[34:35], v[34:35], v[36:37] op_sel_hi:[0,1]
	ds_read_b128 v[36:39], v244 offset:192
	ds_read_b128 v[40:43], v244 offset:448
	v_mov_b32_e32 v17, v31
	v_mov_b32_e32 v3, v13
	s_waitcnt lgkmcnt(0)
	v_pk_fma_f32 v[34:35], v[36:37], v[34:35], v[40:41]
	s_nop 0
	v_pk_fma_f32 v[4:5], v[34:35], s[72:73], v[4:5] op_sel_hi:[1,0,1]
	v_lshlrev_b32_e32 v35, 16, v30
	v_lshlrev_b32_e32 v34, 16, v22
	v_mov_b32_e32 v19, v35
	v_pk_fma_f32 v[32:33], v[38:39], v[32:33], v[42:43]
	v_pk_mul_f32 v[36:37], v[34:35], v[34:35]
	v_pk_mul_f32 v[38:39], v[18:19], v[18:19]
	v_and_b32_e32 v30, 0xffff0000, v23
	v_pk_mul_f32 v[22:23], v[16:17], v[16:17]
	v_pk_mul_f32 v[40:41], v[30:31], v[30:31]
	v_pk_mov_b32 v[42:43], v[34:35], v[36:37] op_sel:[1,0]
	v_pk_mov_b32 v[38:39], v[30:31], v[38:39] op_sel:[1,0]
	v_pk_add_f32 v[18:19], v[34:35], v[18:19]
	v_pk_add_f32 v[16:17], v[30:31], v[16:17]
	v_pk_fma_f32 v[6:7], v[32:33], s[72:73], v[6:7] op_sel_hi:[1,0,1]
	v_pk_add_f32 v[38:39], v[42:43], v[38:39]
	v_mov_b32_e32 v42, v14
	v_mov_b32_e32 v43, v22
	v_pk_mov_b32 v[14:15], v[14:15], v[40:41] op_sel:[1,0]
	v_mov_b32_e32 v19, v37
	v_mov_b32_e32 v17, v41
	v_cvt_pk_bf16_f32 v4, v4, v5
	v_cvt_pk_bf16_f32 v5, v6, v7
	v_pk_add_f32 v[14:15], v[42:43], v[14:15]
	v_pk_add_f32 v[16:17], v[18:19], v[16:17]
	global_store_dwordx2 v[28:29], v[4:5], off offset:288
	v_lshlrev_b32_e32 v28, 16, v4
	v_and_b32_e32 v32, 0xffff0000, v4
	v_lshlrev_b32_e32 v4, 16, v5
	v_and_b32_e32 v6, 0xffff0000, v5
	v_pk_add_f32 v[14:15], v[38:39], v[14:15]
	v_pk_add_f32 v[12:13], v[16:17], v[2:3]
	v_mul_f32_e32 v29, v28, v28
	v_mul_f32_e32 v33, v32, v32
	v_mul_f32_e32 v5, v4, v4
	v_mul_f32_e32 v7, v6, v6
	v_pk_add_f32 v[12:13], v[14:15], v[12:13]
	v_pk_add_f32 v[14:15], v[24:25], v[26:27]
	v_pk_add_f32 v[10:11], v[28:29], v[32:33]
	v_pk_add_f32 v[8:9], v[14:15], v[8:9]
	v_pk_add_f32 v[4:5], v[4:5], v[6:7]
	v_pk_add_f32 v[8:9], v[12:13], v[8:9]
	v_pk_add_f32 v[4:5], v[10:11], v[4:5]
	s_nop 0
	v_pk_add_f32 v[4:5], v[8:9], v[4:5]
	ds_bpermute_b32 v6, v181, v4
	ds_bpermute_b32 v7, v181, v5
	s_waitcnt lgkmcnt(0)
	v_pk_add_f32 v[4:5], v[4:5], v[6:7]
	ds_bpermute_b32 v6, v180, v4
	ds_bpermute_b32 v7, v180, v5
	s_and_saveexec_b64 s[0:1], s[40:41]
	s_cbranch_execz .LBB0_2219
	v_lshl_add_u64 v[8:9], s[50:51], 0, v[20:21]
	v_lshl_add_u64 v[8:9], s[60:61], 2, v[8:9]
	s_waitcnt lgkmcnt(0)
	v_pk_add_f32 v[4:5], v[4:5], v[6:7]
	global_store_dwordx2 v[8:9], v[4:5], off
